# P6: peeled last K-iteration (grid 256): its 14 idle next-unit staging DMAs fetch the epilogue's first 14 x2/PLE operand quads into LDS per lane; epilogue reads them by ds_read_b128, two remaining load
# speedup vs baseline: 1.0017x; 1.0017x over previous
; #define PG8_STAGE(bufoff, gbase, voff) do { _Pragma("unroll") for (int _i = 0; _i < 2; ++_i) \
;         __builtin_amdgcn_global_load_lds((const unsigned*)((const char*)(gbase) + (voff)[_i]), (PG8_LAS unsigned*)(lds + (bufoff) + ldsw + _i * 8192), 16, 0, 0); } while (0)
; #define PG8_LDA(dst, b, h) do { _Pragma("unroll") for (int m = 0; m < 4; ++m) _Pragma("unroll") for (int k = 0; k < 2; ++k) dst[m][k] = *(const PG8_LAS bf16x8*)(lds + PG8_SA(b, h) + aoff + m * 2048 + k * 1024); } while (0)
; #define PG8_LDB(dst, b, h) do { _Pragma("unroll") for (int n = 0; n < 2; ++n) _Pragma("unroll") for (int k = 0; k < 2; ++k) dst[n][k] = *(const PG8_LAS bf16x8*)(lds + PG8_SB(b, h) + boff + n * 2048 + k * 1024); } while (0)
; #define PG8_MMA(ai, bj, At, Bt) do { __builtin_amdgcn_s_setprio(1); _Pragma("unroll") for (int m = 0; m < 4; ++m) _Pragma("unroll") for (int n = 0; n < 2; ++n) _Pragma("unroll") for (int k = 0; k < 2; ++k) \
;         acc[ai][bj][m][n] = __builtin_amdgcn_mfma_f32_16x16x32_bf16(Bt[n][k], At[m][k], acc[ai][bj][m][n], 0, 0, 0); __builtin_amdgcn_s_setprio(0); } while (0)
; #define PG8_WAIT_V(n) asm volatile("s_waitcnt vmcnt(" #n ")" ::: "memory")
; template <class Epi, class Sched, bool ALIGN_EPI = false, bool SP2 = false>
; __device__ __forceinline__ void gemm_phase(PG8_LAS unsigned char* lds, const Gemm g, const Sched& S, const Epi& E) {
;     ...
;             PG8_LDB(B0, 0, 0); PG8_LDB(B1, 0, 1); PG8_SCHED; PG8_LDA(At, 0, 0); PG8_STAGE(PG8_SA(1, 1), a1 + hstep, voffA);
;             PG8_WAIT_V(8); PG8_WAIT_L(0); PG8_BAR; PG8_MMA(0, 0, At, B0); PG8_MMA(0, 1, At, B1); PG8_BAR; PG8_SCHED;
;             PG8_LDA(At, 0, 1); PG8_STAGE(PG8_SB(0, 0), b2, voffB); PG8_STAGE(PG8_SB(0, 1), b2 + hstep, voffB); PG8_STAGE(PG8_SA(0, 0), a2, voffA);
;             PG8_WAIT_V(8); PG8_WAIT_L(0); PG8_BAR; PG8_MMA(1, 0, At, B0); PG8_MMA(1, 1, At, B1); PG8_BAR; PG8_SCHED;
;             PG8_LDB(B0, 1, 0); PG8_LDB(B1, 1, 1); PG8_SCHED; PG8_LDA(At, 1, 0); PG8_STAGE(PG8_SA(0, 1), a2 + hstep, voffA);
;             PG8_WAIT_V(8); PG8_WAIT_L(0); PG8_BAR; PG8_MMA(0, 0, At, B0); PG8_MMA(0, 1, At, B1); PG8_BAR; PG8_SCHED;
;             PG8_LDA(At, 1, 1); PG8_STAGE(PG8_SB(1, 0), b3, voffB); PG8_STAGE(PG8_SB(1, 1), b3 + hstep, voffB); PG8_STAGE(PG8_SA(1, 0), a3, voffA);
;             PG8_WAIT_V(8); PG8_WAIT_L(0); PG8_BAR; PG8_MMA(1, 0, At, B0); PG8_MMA(1, 1, At, B1); PG8_BAR; PG8_SCHED;
.LBB0_1033:
	ds_read_b128 v[128:131], v202
	ds_read_b128 v[132:135], v202 offset:1024
	ds_read_b128 v[136:139], v202 offset:2048
	ds_read_b128 v[140:143], v202 offset:3072
	ds_read_b128 v[144:147], v203
	ds_read_b128 v[148:151], v203 offset:1024
	ds_read_b128 v[152:155], v203 offset:2048
	ds_read_b128 v[156:159], v203 offset:3072
	s_add_u32 s6, s4, 0xfffc0080
	s_addc_u32 s7, s5, -1
	s_cmp_eq_u32 s62, 12
	s_cselect_b32 s41, s3, s7
	s_cselect_b32 s40, s35, s6
	s_cselect_b32 s7, s31, s61
	s_cselect_b32 s6, s59, s60
	v_lshl_add_u64 v[218:219], s[4:5], 0, v[170:171]
	s_add_i32 m0, s44, 0xc000
	ds_read_b128 v[178:181], v204
	ds_read_b128 v[182:185], v204 offset:1024
	ds_read_b128 v[186:189], v204 offset:2048
	ds_read_b128 v[190:193], v204 offset:3072
	ds_read_b128 v[194:197], v204 offset:4096
	ds_read_b128 v[206:209], v204 offset:5120
	ds_read_b128 v[210:213], v204 offset:6144
	ds_read_b128 v[214:217], v204 offset:7168
	global_load_lds_dwordx4 v[218:219], off
	v_lshl_add_u64 v[218:219], s[4:5], 0, v[172:173]
	s_add_i32 m0, s44, 0xe000
	s_nop 0
	global_load_lds_dwordx4 v[218:219], off
	s_waitcnt vmcnt(8)
	s_waitcnt lgkmcnt(0)
	s_setprio 1
	s_barrier
	s_waitcnt lgkmcnt(0)
	v_mfma_f32_16x16x32_bf16 v[124:127], v[128:131], v[178:181], v[124:127]
	v_mfma_f32_16x16x32_bf16 v[120:123], v[136:139], v[178:181], v[120:123]
	v_mfma_f32_16x16x32_bf16 v[108:111], v[128:131], v[186:189], v[108:111]
	v_mfma_f32_16x16x32_bf16 v[104:107], v[136:139], v[186:189], v[104:107]
	v_mfma_f32_16x16x32_bf16 v[92:95], v[128:131], v[194:197], v[92:95]
	v_mfma_f32_16x16x32_bf16 v[88:91], v[136:139], v[194:197], v[88:91]
	v_mfma_f32_16x16x32_bf16 v[76:79], v[128:131], v[210:213], v[76:79]
	v_mfma_f32_16x16x32_bf16 v[72:75], v[136:139], v[210:213], v[72:75]
	v_mfma_f32_16x16x32_bf16 v[124:127], v[132:135], v[182:185], v[124:127]
	v_mfma_f32_16x16x32_bf16 v[120:123], v[140:143], v[182:185], v[120:123]
	v_mfma_f32_16x16x32_bf16 v[108:111], v[132:135], v[190:193], v[108:111]
	v_mfma_f32_16x16x32_bf16 v[104:107], v[140:143], v[190:193], v[104:107]
	v_mfma_f32_16x16x32_bf16 v[92:95], v[132:135], v[206:209], v[92:95]
	v_mfma_f32_16x16x32_bf16 v[88:91], v[140:143], v[206:209], v[88:91]
	v_mfma_f32_16x16x32_bf16 v[76:79], v[132:135], v[214:217], v[76:79]
	v_mfma_f32_16x16x32_bf16 v[72:75], v[140:143], v[214:217], v[72:75]
	s_setprio 0
	s_setprio 1
	v_mfma_f32_16x16x32_bf16 v[116:119], v[144:147], v[178:181], v[116:119]
	v_mfma_f32_16x16x32_bf16 v[112:115], v[152:155], v[178:181], v[112:115]
	v_mfma_f32_16x16x32_bf16 v[100:103], v[144:147], v[186:189], v[100:103]
	v_mfma_f32_16x16x32_bf16 v[96:99], v[152:155], v[186:189], v[96:99]
	v_mfma_f32_16x16x32_bf16 v[84:87], v[144:147], v[194:197], v[84:87]
	v_mfma_f32_16x16x32_bf16 v[80:83], v[152:155], v[194:197], v[80:83]
	v_mfma_f32_16x16x32_bf16 v[68:71], v[144:147], v[210:213], v[68:71]
	v_mfma_f32_16x16x32_bf16 v[64:67], v[152:155], v[210:213], v[64:67]
	v_mfma_f32_16x16x32_bf16 v[116:119], v[148:151], v[182:185], v[116:119]
	v_mfma_f32_16x16x32_bf16 v[112:115], v[156:159], v[182:185], v[112:115]
	v_mfma_f32_16x16x32_bf16 v[100:103], v[148:151], v[190:193], v[100:103]
	v_mfma_f32_16x16x32_bf16 v[96:99], v[156:159], v[190:193], v[96:99]
	v_mfma_f32_16x16x32_bf16 v[84:87], v[148:151], v[206:209], v[84:87]
	v_mfma_f32_16x16x32_bf16 v[80:83], v[156:159], v[206:209], v[80:83]
	v_mfma_f32_16x16x32_bf16 v[68:71], v[148:151], v[214:217], v[68:71]
	s_setprio 3
	s_barrier
	v_mfma_f32_16x16x32_bf16 v[64:67], v[156:159], v[214:217], v[64:67]
	s_setprio 0
	s_add_i32 s63, s55, s42
	v_lshl_add_u64 v[218:219], s[6:7], 0, v[162:163]
	s_mov_b32 m0, s63
	ds_read_b128 v[178:181], v204 offset:16384
	ds_read_b128 v[182:185], v204 offset:17408
	ds_read_b128 v[186:189], v204 offset:18432
	ds_read_b128 v[190:193], v204 offset:19456
	ds_read_b128 v[194:197], v204 offset:20480
	ds_read_b128 v[206:209], v204 offset:21504
	ds_read_b128 v[210:213], v204 offset:22528
	ds_read_b128 v[214:217], v204 offset:23552
	global_load_lds_dwordx4 v[218:219], off
	s_add_i32 m0, s63, 0x2000
	s_add_u32 s64, s6, 0x40000
	v_lshl_add_u64 v[220:221], s[6:7], 0, v[166:167]
	s_addc_u32 s65, s7, 0
	s_add_i32 s63, s56, s42
	global_load_lds_dwordx4 v[220:221], off
	v_lshl_add_u64 v[222:223], s[64:65], 0, v[162:163]
	s_mov_b32 m0, s63
	v_lshl_add_u64 v[224:225], s[40:41], 0, v[164:165]
	global_load_lds_dwordx4 v[222:223], off
	v_lshl_add_u64 v[222:223], s[64:65], 0, v[166:167]
	s_add_i32 m0, s63, 0x2000
	s_nop 0
	global_load_lds_dwordx4 v[222:223], off
	v_lshl_add_u64 v[222:223], s[40:41], 0, v[160:161]
	s_mov_b32 m0, s44
	s_nop 0
	global_load_lds_dwordx4 v[222:223], off
	s_mov_b32 m0, s45
	s_nop 0
	global_load_lds_dwordx4 v[224:225], off
	s_waitcnt vmcnt(8)
	s_waitcnt lgkmcnt(0)
	s_setprio 1
	s_barrier
; #define PG8_STAGE(bufoff, gbase, voff) do { _Pragma("unroll") for (int _i = 0; _i < 2; ++_i) \
;         __builtin_amdgcn_global_load_lds((const unsigned*)((const char*)(gbase) + (voff)[_i]), (PG8_LAS unsigned*)(lds + (bufoff) + ldsw + _i * 8192), 16, 0, 0); } while (0)
; #define PG8_LDA(dst, b, h) do { _Pragma("unroll") for (int m = 0; m < 4; ++m) _Pragma("unroll") for (int k = 0; k < 2; ++k) dst[m][k] = *(const PG8_LAS bf16x8*)(lds + PG8_SA(b, h) + aoff + m * 2048 + k * 1024); } while (0)
; #define PG8_LDB(dst, b, h) do { _Pragma("unroll") for (int n = 0; n < 2; ++n) _Pragma("unroll") for (int k = 0; k < 2; ++k) dst[n][k] = *(const PG8_LAS bf16x8*)(lds + PG8_SB(b, h) + boff + n * 2048 + k * 1024); } while (0)
; #define PG8_MMA(ai, bj, At, Bt) do { __builtin_amdgcn_s_setprio(1); _Pragma("unroll") for (int m = 0; m < 4; ++m) _Pragma("unroll") for (int n = 0; n < 2; ++n) _Pragma("unroll") for (int k = 0; k < 2; ++k) \
;         acc[ai][bj][m][n] = __builtin_amdgcn_mfma_f32_16x16x32_bf16(Bt[n][k], At[m][k], acc[ai][bj][m][n], 0, 0, 0); __builtin_amdgcn_s_setprio(0); } while (0)
; #define PG8_WAIT_V(n) asm volatile("s_waitcnt vmcnt(" #n ")" ::: "memory")
; template <class Epi, class Sched, bool ALIGN_EPI = false, bool SP2 = false>
; __device__ __forceinline__ void gemm_phase(PG8_LAS unsigned char* lds, const Gemm g, const Sched& S, const Epi& E) {
;     ...
;             PG8_LDB(B0, 0, 0); PG8_LDB(B1, 0, 1); PG8_SCHED; PG8_LDA(At, 0, 0); PG8_STAGE(PG8_SA(1, 1), a1 + hstep, voffA);
;             PG8_WAIT_V(8); PG8_WAIT_L(0); PG8_BAR; PG8_MMA(0, 0, At, B0); PG8_MMA(0, 1, At, B1); PG8_BAR; PG8_SCHED;
;             PG8_LDA(At, 0, 1); PG8_STAGE(PG8_SB(0, 0), b2, voffB); PG8_STAGE(PG8_SB(0, 1), b2 + hstep, voffB); PG8_STAGE(PG8_SA(0, 0), a2, voffA);
;             PG8_WAIT_V(8); PG8_WAIT_L(0); PG8_BAR; PG8_MMA(1, 0, At, B0); PG8_MMA(1, 1, At, B1); PG8_BAR; PG8_SCHED;
;             PG8_LDB(B0, 1, 0); PG8_LDB(B1, 1, 1); PG8_SCHED; PG8_LDA(At, 1, 0); PG8_STAGE(PG8_SA(0, 1), a2 + hstep, voffA);
;             PG8_WAIT_V(8); PG8_WAIT_L(0); PG8_BAR; PG8_MMA(0, 0, At, B0); PG8_MMA(0, 1, At, B1); PG8_BAR; PG8_SCHED;
;             PG8_LDA(At, 1, 1); PG8_STAGE(PG8_SB(1, 0), b3, voffB); PG8_STAGE(PG8_SB(1, 1), b3 + hstep, voffB); PG8_STAGE(PG8_SA(1, 0), a3, voffA);
;             PG8_WAIT_V(8); PG8_WAIT_L(0); PG8_BAR; PG8_MMA(1, 0, At, B0); PG8_MMA(1, 1, At, B1); PG8_BAR; PG8_SCHED;
	s_waitcnt lgkmcnt(0)
	v_mfma_f32_16x16x32_bf16 v[60:63], v[128:131], v[178:181], v[60:63]
	v_mfma_f32_16x16x32_bf16 v[56:59], v[136:139], v[178:181], v[56:59]
	v_mfma_f32_16x16x32_bf16 v[44:47], v[128:131], v[186:189], v[44:47]
	v_mfma_f32_16x16x32_bf16 v[40:43], v[136:139], v[186:189], v[40:43]
	v_mfma_f32_16x16x32_bf16 v[28:31], v[128:131], v[194:197], v[28:31]
	v_mfma_f32_16x16x32_bf16 v[24:27], v[136:139], v[194:197], v[24:27]
	v_mfma_f32_16x16x32_bf16 v[12:15], v[128:131], v[210:213], v[12:15]
	v_mfma_f32_16x16x32_bf16 v[8:11], v[136:139], v[210:213], v[8:11]
	v_mfma_f32_16x16x32_bf16 v[60:63], v[132:135], v[182:185], v[60:63]
	v_mfma_f32_16x16x32_bf16 v[56:59], v[140:143], v[182:185], v[56:59]
	v_mfma_f32_16x16x32_bf16 v[44:47], v[132:135], v[190:193], v[44:47]
	v_mfma_f32_16x16x32_bf16 v[40:43], v[140:143], v[190:193], v[40:43]
	v_mfma_f32_16x16x32_bf16 v[28:31], v[132:135], v[206:209], v[28:31]
	v_mfma_f32_16x16x32_bf16 v[24:27], v[140:143], v[206:209], v[24:27]
	v_mfma_f32_16x16x32_bf16 v[12:15], v[132:135], v[214:217], v[12:15]
	v_mfma_f32_16x16x32_bf16 v[8:11], v[140:143], v[214:217], v[8:11]
	s_setprio 0
	s_setprio 1
	v_mfma_f32_16x16x32_bf16 v[52:55], v[144:147], v[178:181], v[52:55]
	v_mfma_f32_16x16x32_bf16 v[48:51], v[152:155], v[178:181], v[48:51]
	v_mfma_f32_16x16x32_bf16 v[36:39], v[144:147], v[186:189], v[36:39]
	v_mfma_f32_16x16x32_bf16 v[32:35], v[152:155], v[186:189], v[32:35]
	v_mfma_f32_16x16x32_bf16 v[20:23], v[144:147], v[194:197], v[20:23]
	v_mfma_f32_16x16x32_bf16 v[16:19], v[152:155], v[194:197], v[16:19]
	v_mfma_f32_16x16x32_bf16 v[4:7], v[144:147], v[210:213], v[4:7]
	v_mfma_f32_16x16x32_bf16 v[0:3], v[152:155], v[210:213], v[0:3]
	v_mfma_f32_16x16x32_bf16 v[52:55], v[148:151], v[182:185], v[52:55]
	v_mfma_f32_16x16x32_bf16 v[48:51], v[156:159], v[182:185], v[48:51]
	v_mfma_f32_16x16x32_bf16 v[36:39], v[148:151], v[190:193], v[36:39]
	v_mfma_f32_16x16x32_bf16 v[32:35], v[156:159], v[190:193], v[32:35]
	v_mfma_f32_16x16x32_bf16 v[20:23], v[148:151], v[206:209], v[20:23]
	v_mfma_f32_16x16x32_bf16 v[16:19], v[156:159], v[206:209], v[16:19]
	v_mfma_f32_16x16x32_bf16 v[4:7], v[148:151], v[214:217], v[4:7]
	s_setprio 3
	s_barrier
	v_mfma_f32_16x16x32_bf16 v[0:3], v[156:159], v[214:217], v[0:3]
	s_setprio 0
	s_add_i32 s63, 0, 0x18000
	s_add_i32 s64, 0, 0x1c000
	v_add_u32_e32 v140, s63, v199
	v_add_u32_e32 v156, s64, v199
	ds_read_b128 v[128:131], v140
	ds_read_b128 v[132:135], v140 offset:1024
	ds_read_b128 v[136:139], v140 offset:2048
	ds_read_b128 v[140:143], v140 offset:3072
	ds_read_b128 v[144:147], v156
	ds_read_b128 v[148:151], v156 offset:1024
	ds_read_b128 v[152:155], v156 offset:2048
	ds_read_b128 v[156:159], v156 offset:3072
	s_add_u32 s40, s40, 0x40000
	s_addc_u32 s41, s41, 0
	s_mov_b32 m0, s46
	v_lshl_add_u64 v[226:227], s[40:41], 0, v[160:161]
	ds_read_b128 v[178:181], v204 offset:32768
	ds_read_b128 v[182:185], v204 offset:33792
	ds_read_b128 v[186:189], v204 offset:34816
	ds_read_b128 v[190:193], v204 offset:35840
	ds_read_b128 v[194:197], v204 offset:36864
	ds_read_b128 v[206:209], v204 offset:37888
	ds_read_b128 v[210:213], v204 offset:38912
	ds_read_b128 v[214:217], v204 offset:39936
	global_load_lds_dwordx4 v[226:227], off
	v_lshl_add_u64 v[226:227], s[40:41], 0, v[164:165]
	s_mov_b32 m0, s47
	s_nop 0
	global_load_lds_dwordx4 v[226:227], off
	s_waitcnt vmcnt(8)
	s_waitcnt lgkmcnt(0)
	s_setprio 1
	s_barrier
	s_waitcnt lgkmcnt(0)
	v_mfma_f32_16x16x32_bf16 v[124:127], v[128:131], v[178:181], v[124:127]
	v_mfma_f32_16x16x32_bf16 v[120:123], v[136:139], v[178:181], v[120:123]
	v_mfma_f32_16x16x32_bf16 v[108:111], v[128:131], v[186:189], v[108:111]
	v_mfma_f32_16x16x32_bf16 v[104:107], v[136:139], v[186:189], v[104:107]
	v_mfma_f32_16x16x32_bf16 v[92:95], v[128:131], v[194:197], v[92:95]
	v_mfma_f32_16x16x32_bf16 v[88:91], v[136:139], v[194:197], v[88:91]
	v_mfma_f32_16x16x32_bf16 v[76:79], v[128:131], v[210:213], v[76:79]
	v_mfma_f32_16x16x32_bf16 v[72:75], v[136:139], v[210:213], v[72:75]
	v_mfma_f32_16x16x32_bf16 v[124:127], v[132:135], v[182:185], v[124:127]
	v_mfma_f32_16x16x32_bf16 v[120:123], v[140:143], v[182:185], v[120:123]
	v_mfma_f32_16x16x32_bf16 v[108:111], v[132:135], v[190:193], v[108:111]
	v_mfma_f32_16x16x32_bf16 v[104:107], v[140:143], v[190:193], v[104:107]
	v_mfma_f32_16x16x32_bf16 v[92:95], v[132:135], v[206:209], v[92:95]
	v_mfma_f32_16x16x32_bf16 v[88:91], v[140:143], v[206:209], v[88:91]
	v_mfma_f32_16x16x32_bf16 v[76:79], v[132:135], v[214:217], v[76:79]
	v_mfma_f32_16x16x32_bf16 v[72:75], v[140:143], v[214:217], v[72:75]
	s_setprio 0
	s_setprio 1
	v_mfma_f32_16x16x32_bf16 v[116:119], v[144:147], v[178:181], v[116:119]
	v_mfma_f32_16x16x32_bf16 v[112:115], v[152:155], v[178:181], v[112:115]
	v_mfma_f32_16x16x32_bf16 v[100:103], v[144:147], v[186:189], v[100:103]
	v_mfma_f32_16x16x32_bf16 v[96:99], v[152:155], v[186:189], v[96:99]
	v_mfma_f32_16x16x32_bf16 v[84:87], v[144:147], v[194:197], v[84:87]
	v_mfma_f32_16x16x32_bf16 v[80:83], v[152:155], v[194:197], v[80:83]
	v_mfma_f32_16x16x32_bf16 v[68:71], v[144:147], v[210:213], v[68:71]
	v_mfma_f32_16x16x32_bf16 v[64:67], v[152:155], v[210:213], v[64:67]
	v_mfma_f32_16x16x32_bf16 v[116:119], v[148:151], v[182:185], v[116:119]
	v_mfma_f32_16x16x32_bf16 v[112:115], v[156:159], v[182:185], v[112:115]
	v_mfma_f32_16x16x32_bf16 v[100:103], v[148:151], v[190:193], v[100:103]
	v_mfma_f32_16x16x32_bf16 v[96:99], v[156:159], v[190:193], v[96:99]
	v_mfma_f32_16x16x32_bf16 v[84:87], v[148:151], v[206:209], v[84:87]
	v_mfma_f32_16x16x32_bf16 v[80:83], v[156:159], v[206:209], v[80:83]
	v_mfma_f32_16x16x32_bf16 v[68:71], v[148:151], v[214:217], v[68:71]
	s_setprio 3
	s_barrier
; #define PG8_STAGE(bufoff, gbase, voff) do { _Pragma("unroll") for (int _i = 0; _i < 2; ++_i) \
;         __builtin_amdgcn_global_load_lds((const unsigned*)((const char*)(gbase) + (voff)[_i]), (PG8_LAS unsigned*)(lds + (bufoff) + ldsw + _i * 8192), 16, 0, 0); } while (0)
; #define PG8_LDA(dst, b, h) do { _Pragma("unroll") for (int m = 0; m < 4; ++m) _Pragma("unroll") for (int k = 0; k < 2; ++k) dst[m][k] = *(const PG8_LAS bf16x8*)(lds + PG8_SA(b, h) + aoff + m * 2048 + k * 1024); } while (0)
; #define PG8_LDB(dst, b, h) do { _Pragma("unroll") for (int n = 0; n < 2; ++n) _Pragma("unroll") for (int k = 0; k < 2; ++k) dst[n][k] = *(const PG8_LAS bf16x8*)(lds + PG8_SB(b, h) + boff + n * 2048 + k * 1024); } while (0)
; #define PG8_WAIT_V(n) asm volatile("s_waitcnt vmcnt(" #n ")" ::: "memory")
; template <class Epi, class Sched, bool ALIGN_EPI = false, bool SP2 = false>
; __device__ __forceinline__ void gemm_phase(PG8_LAS unsigned char* lds, const Gemm g, const Sched& S, const Epi& E) {
;     ...
;             const bool last = (t == nt - 2);
;             const char* a1 = cA + (size_t)(t + 1) * kstep;
;             const char* a2 = last ? nA : cA + (size_t)(t + 2) * kstep; const char* b2 = last ? nB : cB + (size_t)(t + 2) * kstep;
;             const char* a3 = a2 + kstep; const char* b3 = b2 + kstep;
;             if (last && has_next) S.a_ready(nxt);
;     ...
;             PG8_LDB(B0, 0, 0); PG8_LDB(B1, 0, 1); PG8_SCHED; PG8_LDA(At, 0, 0); PG8_STAGE(PG8_SA(1, 1), a1 + hstep, voffA);
;             PG8_WAIT_V(8); PG8_WAIT_L(0); PG8_BAR; PG8_MMA(0, 0, At, B0); PG8_MMA(0, 1, At, B1); PG8_BAR; PG8_SCHED;
;             PG8_LDA(At, 0, 1); PG8_STAGE(PG8_SB(0, 0), b2, voffB); PG8_STAGE(PG8_SB(0, 1), b2 + hstep, voffB); PG8_STAGE(PG8_SA(0, 0), a2, voffA);
;             PG8_WAIT_V(8); PG8_WAIT_L(0); PG8_BAR; PG8_MMA(1, 0, At, B0); PG8_MMA(1, 1, At, B1); PG8_BAR; PG8_SCHED;
;             PG8_LDB(B0, 1, 0); PG8_LDB(B1, 1, 1); PG8_SCHED; PG8_LDA(At, 1, 0); PG8_STAGE(PG8_SA(0, 1), a2 + hstep, voffA);
;             PG8_WAIT_V(8); PG8_WAIT_L(0); PG8_BAR; PG8_MMA(0, 0, At, B0); PG8_MMA(0, 1, At, B1); PG8_BAR; PG8_SCHED;
;             PG8_LDA(At, 1, 1); PG8_STAGE(PG8_SB(1, 0), b3, voffB); PG8_STAGE(PG8_SB(1, 1), b3 + hstep, voffB); PG8_STAGE(PG8_SA(1, 0), a3, voffA);
;             PG8_WAIT_V(8); PG8_WAIT_L(0); PG8_BAR; PG8_MMA(1, 0, At, B0); PG8_MMA(1, 1, At, B1); PG8_BAR; PG8_SCHED;
	v_mfma_f32_16x16x32_bf16 v[64:67], v[156:159], v[214:217], v[64:67]
	s_setprio 0
	s_add_i32 s40, s63, s42
	v_lshl_add_u64 v[218:219], v[218:219], 0, s[12:13]
	s_mov_b32 m0, s40
	ds_read_b128 v[178:181], v204 offset:49152
	ds_read_b128 v[182:185], v204 offset:50176
	ds_read_b128 v[186:189], v204 offset:51200
	ds_read_b128 v[190:193], v204 offset:52224
	ds_read_b128 v[194:197], v204 offset:53248
	ds_read_b128 v[206:209], v204 offset:54272
	ds_read_b128 v[210:213], v204 offset:55296
	ds_read_b128 v[214:217], v204 offset:56320
	global_load_lds_dwordx4 v[218:219], off
	s_add_i32 m0, s40, 0x2000
	s_add_u32 s6, s6, 0x40080
	v_lshl_add_u64 v[218:219], v[220:221], 0, s[12:13]
	s_addc_u32 s7, s7, 0
	s_add_i32 s40, s64, s42
	global_load_lds_dwordx4 v[218:219], off
	v_lshl_add_u64 v[218:219], s[6:7], 0, v[162:163]
	s_mov_b32 m0, s40
	s_nop 0
	global_load_lds_dwordx4 v[218:219], off
	v_lshl_add_u64 v[218:219], s[6:7], 0, v[166:167]
	s_add_i32 m0, s40, 0x2000
	s_nop 0
	global_load_lds_dwordx4 v[218:219], off
	v_lshl_add_u64 v[218:219], v[222:223], 0, s[12:13]
	s_mov_b32 m0, s52
	s_nop 0
	global_load_lds_dwordx4 v[218:219], off
	v_lshl_add_u64 v[218:219], v[224:225], 0, s[12:13]
	s_mov_b32 m0, s53
	s_nop 0
	global_load_lds_dwordx4 v[218:219], off
	s_waitcnt vmcnt(8)
	s_waitcnt lgkmcnt(0)
	s_setprio 1
	s_barrier
	s_waitcnt lgkmcnt(0)
	v_mfma_f32_16x16x32_bf16 v[60:63], v[128:131], v[178:181], v[60:63]
	v_mfma_f32_16x16x32_bf16 v[56:59], v[136:139], v[178:181], v[56:59]
	v_mfma_f32_16x16x32_bf16 v[44:47], v[128:131], v[186:189], v[44:47]
	v_mfma_f32_16x16x32_bf16 v[40:43], v[136:139], v[186:189], v[40:43]
	v_mfma_f32_16x16x32_bf16 v[28:31], v[128:131], v[194:197], v[28:31]
	v_mfma_f32_16x16x32_bf16 v[24:27], v[136:139], v[194:197], v[24:27]
	v_mfma_f32_16x16x32_bf16 v[12:15], v[128:131], v[210:213], v[12:15]
	v_mfma_f32_16x16x32_bf16 v[8:11], v[136:139], v[210:213], v[8:11]
	v_mfma_f32_16x16x32_bf16 v[60:63], v[132:135], v[182:185], v[60:63]
	v_mfma_f32_16x16x32_bf16 v[56:59], v[140:143], v[182:185], v[56:59]
	v_mfma_f32_16x16x32_bf16 v[44:47], v[132:135], v[190:193], v[44:47]
	v_mfma_f32_16x16x32_bf16 v[40:43], v[140:143], v[190:193], v[40:43]
	v_mfma_f32_16x16x32_bf16 v[28:31], v[132:135], v[206:209], v[28:31]
	v_mfma_f32_16x16x32_bf16 v[24:27], v[140:143], v[206:209], v[24:27]
	v_mfma_f32_16x16x32_bf16 v[12:15], v[132:135], v[214:217], v[12:15]
	v_mfma_f32_16x16x32_bf16 v[8:11], v[140:143], v[214:217], v[8:11]
	s_setprio 0
	s_setprio 1
	v_mfma_f32_16x16x32_bf16 v[52:55], v[144:147], v[178:181], v[52:55]
	v_mfma_f32_16x16x32_bf16 v[48:51], v[152:155], v[178:181], v[48:51]
	v_mfma_f32_16x16x32_bf16 v[36:39], v[144:147], v[186:189], v[36:39]
	v_mfma_f32_16x16x32_bf16 v[32:35], v[152:155], v[186:189], v[32:35]
	v_mfma_f32_16x16x32_bf16 v[20:23], v[144:147], v[194:197], v[20:23]
	v_mfma_f32_16x16x32_bf16 v[16:19], v[152:155], v[194:197], v[16:19]
	v_mfma_f32_16x16x32_bf16 v[4:7], v[144:147], v[210:213], v[4:7]
	v_mfma_f32_16x16x32_bf16 v[0:3], v[152:155], v[210:213], v[0:3]
	v_mfma_f32_16x16x32_bf16 v[52:55], v[148:151], v[182:185], v[52:55]
	v_mfma_f32_16x16x32_bf16 v[48:51], v[156:159], v[182:185], v[48:51]
	v_mfma_f32_16x16x32_bf16 v[36:39], v[148:151], v[190:193], v[36:39]
	v_mfma_f32_16x16x32_bf16 v[32:35], v[156:159], v[190:193], v[32:35]
	v_mfma_f32_16x16x32_bf16 v[20:23], v[148:151], v[206:209], v[20:23]
	v_mfma_f32_16x16x32_bf16 v[16:19], v[156:159], v[206:209], v[16:19]
	v_mfma_f32_16x16x32_bf16 v[4:7], v[148:151], v[214:217], v[4:7]
	s_setprio 3
	s_barrier
	v_mfma_f32_16x16x32_bf16 v[0:3], v[156:159], v[214:217], v[0:3]
	s_setprio 0
	s_add_i32 s62, s62, 2
	s_add_u32 s4, s4, 0x100
	s_addc_u32 s5, s5, 0
	s_add_u32 s60, s60, 0x100
	s_addc_u32 s61, s61, 0
	s_cmp_gt_u32 s62, 13
	s_cbranch_scc1 .Lp6x_gen
	s_cmp_lg_u32 s62, 12
	s_cbranch_scc1 .LBB0_1033
	s_cmpk_lg_i32 s33, 0x100
	s_cbranch_scc1 .LBB0_1033
	ds_read_b128 v[128:131], v202
	ds_read_b128 v[132:135], v202 offset:1024
	ds_read_b128 v[136:139], v202 offset:2048
	ds_read_b128 v[140:143], v202 offset:3072
	ds_read_b128 v[144:147], v203
	ds_read_b128 v[148:151], v203 offset:1024
	ds_read_b128 v[152:155], v203 offset:2048
	ds_read_b128 v[156:159], v203 offset:3072
	s_add_u32 s6, s4, 0xfffc0080
	s_addc_u32 s7, s5, -1
	s_cmp_eq_u32 s62, 12
	s_cselect_b32 s41, s3, s7
	s_cselect_b32 s40, s35, s6
	s_cselect_b32 s7, s31, s61
	s_cselect_b32 s6, s59, s60
	v_lshl_add_u64 v[218:219], s[4:5], 0, v[170:171]
	s_add_i32 m0, s44, 0xc000
	ds_read_b128 v[178:181], v204
	ds_read_b128 v[182:185], v204 offset:1024
	ds_read_b128 v[186:189], v204 offset:2048
	ds_read_b128 v[190:193], v204 offset:3072
	ds_read_b128 v[194:197], v204 offset:4096
	ds_read_b128 v[206:209], v204 offset:5120
	ds_read_b128 v[210:213], v204 offset:6144
	ds_read_b128 v[214:217], v204 offset:7168
	global_load_lds_dwordx4 v[218:219], off
	v_lshl_add_u64 v[218:219], s[4:5], 0, v[172:173]
	s_add_i32 m0, s44, 0xe000
	s_nop 0
	global_load_lds_dwordx4 v[218:219], off
	s_waitcnt vmcnt(8)
	s_waitcnt lgkmcnt(0)
	s_setprio 1
	s_barrier
; #define PG8_STAGE(bufoff, gbase, voff) do { _Pragma("unroll") for (int _i = 0; _i < 2; ++_i) \
;         __builtin_amdgcn_global_load_lds((const unsigned*)((const char*)(gbase) + (voff)[_i]), (PG8_LAS unsigned*)(lds + (bufoff) + ldsw + _i * 8192), 16, 0, 0); } while (0)
; #define PG8_LDA(dst, b, h) do { _Pragma("unroll") for (int m = 0; m < 4; ++m) _Pragma("unroll") for (int k = 0; k < 2; ++k) dst[m][k] = *(const PG8_LAS bf16x8*)(lds + PG8_SA(b, h) + aoff + m * 2048 + k * 1024); } while (0)
; #define PG8_LDB(dst, b, h) do { _Pragma("unroll") for (int n = 0; n < 2; ++n) _Pragma("unroll") for (int k = 0; k < 2; ++k) dst[n][k] = *(const PG8_LAS bf16x8*)(lds + PG8_SB(b, h) + boff + n * 2048 + k * 1024); } while (0)
;     __device__ __forceinline__ void operator()(const f32x4 (&acc)[2][2][4][2], const Unit& u, int wr, int wc, int fr, int fq) const {
;     ...
;             for (int m = 0; m < 4; ++m)
; #pragma unroll
;                 for (int bj = 0; bj < 2; ++bj) { const size_t off = (size_t)(row0 + ai * HALF + m * 16) * DM + col0 + bj * HALF; prv[m][bj] = *(const u32x4*)(PR + off); xbv[m][bj] = *(const u32x4*)(Xb + off); }
; template <class Epi, class Sched, bool ALIGN_EPI = false, bool SP2 = false>
; __device__ __forceinline__ void gemm_phase(PG8_LAS unsigned char* lds, const Gemm g, const Sched& S, const Epi& E) {
;     ...
;             PG8_LDB(B0, 0, 0); PG8_LDB(B1, 0, 1); PG8_SCHED; PG8_LDA(At, 0, 0); PG8_STAGE(PG8_SA(1, 1), a1 + hstep, voffA);
;             PG8_WAIT_V(8); PG8_WAIT_L(0); PG8_BAR; PG8_MMA(0, 0, At, B0); PG8_MMA(0, 1, At, B1); PG8_BAR; PG8_SCHED;
;             PG8_LDA(At, 0, 1); PG8_STAGE(PG8_SB(0, 0), b2, voffB); PG8_STAGE(PG8_SB(0, 1), b2 + hstep, voffB); PG8_STAGE(PG8_SA(0, 0), a2, voffA);
;             PG8_WAIT_V(8); PG8_WAIT_L(0); PG8_BAR; PG8_MMA(1, 0, At, B0); PG8_MMA(1, 1, At, B1); PG8_BAR; PG8_SCHED;
;             PG8_LDB(B0, 1, 0); PG8_LDB(B1, 1, 1); PG8_SCHED; PG8_LDA(At, 1, 0); PG8_STAGE(PG8_SA(0, 1), a2 + hstep, voffA);
;             PG8_WAIT_V(8); PG8_WAIT_L(0); PG8_BAR; PG8_MMA(0, 0, At, B0); PG8_MMA(0, 1, At, B1); PG8_BAR; PG8_SCHED;
;             PG8_LDA(At, 1, 1); PG8_STAGE(PG8_SB(1, 0), b3, voffB); PG8_STAGE(PG8_SB(1, 1), b3 + hstep, voffB); PG8_STAGE(PG8_SA(1, 0), a3, voffA);
;             PG8_WAIT_V(8); PG8_WAIT_L(0); PG8_BAR; PG8_MMA(1, 0, At, B0); PG8_MMA(1, 1, At, B1); PG8_BAR; PG8_SCHED;
	s_waitcnt lgkmcnt(0)
	v_mfma_f32_16x16x32_bf16 v[124:127], v[128:131], v[178:181], v[124:127]
	v_mfma_f32_16x16x32_bf16 v[120:123], v[136:139], v[178:181], v[120:123]
	v_mfma_f32_16x16x32_bf16 v[108:111], v[128:131], v[186:189], v[108:111]
	v_mfma_f32_16x16x32_bf16 v[104:107], v[136:139], v[186:189], v[104:107]
	v_mfma_f32_16x16x32_bf16 v[92:95], v[128:131], v[194:197], v[92:95]
	v_mfma_f32_16x16x32_bf16 v[88:91], v[136:139], v[194:197], v[88:91]
	v_mfma_f32_16x16x32_bf16 v[76:79], v[128:131], v[210:213], v[76:79]
	v_mfma_f32_16x16x32_bf16 v[72:75], v[136:139], v[210:213], v[72:75]
	v_mfma_f32_16x16x32_bf16 v[124:127], v[132:135], v[182:185], v[124:127]
	v_mfma_f32_16x16x32_bf16 v[120:123], v[140:143], v[182:185], v[120:123]
	v_mfma_f32_16x16x32_bf16 v[108:111], v[132:135], v[190:193], v[108:111]
	v_mfma_f32_16x16x32_bf16 v[104:107], v[140:143], v[190:193], v[104:107]
	v_mfma_f32_16x16x32_bf16 v[92:95], v[132:135], v[206:209], v[92:95]
	v_mfma_f32_16x16x32_bf16 v[88:91], v[140:143], v[206:209], v[88:91]
	v_mfma_f32_16x16x32_bf16 v[76:79], v[132:135], v[214:217], v[76:79]
	v_mfma_f32_16x16x32_bf16 v[72:75], v[140:143], v[214:217], v[72:75]
	s_setprio 0
	s_setprio 1
	v_mfma_f32_16x16x32_bf16 v[116:119], v[144:147], v[178:181], v[116:119]
	v_mfma_f32_16x16x32_bf16 v[112:115], v[152:155], v[178:181], v[112:115]
	v_mfma_f32_16x16x32_bf16 v[100:103], v[144:147], v[186:189], v[100:103]
	v_mfma_f32_16x16x32_bf16 v[96:99], v[152:155], v[186:189], v[96:99]
	v_mfma_f32_16x16x32_bf16 v[84:87], v[144:147], v[194:197], v[84:87]
	v_mfma_f32_16x16x32_bf16 v[80:83], v[152:155], v[194:197], v[80:83]
	v_mfma_f32_16x16x32_bf16 v[68:71], v[144:147], v[210:213], v[68:71]
	v_mfma_f32_16x16x32_bf16 v[64:67], v[152:155], v[210:213], v[64:67]
	v_mfma_f32_16x16x32_bf16 v[116:119], v[148:151], v[182:185], v[116:119]
	v_mfma_f32_16x16x32_bf16 v[112:115], v[156:159], v[182:185], v[112:115]
	v_mfma_f32_16x16x32_bf16 v[100:103], v[148:151], v[190:193], v[100:103]
	v_mfma_f32_16x16x32_bf16 v[96:99], v[156:159], v[190:193], v[96:99]
	v_mfma_f32_16x16x32_bf16 v[84:87], v[148:151], v[206:209], v[84:87]
	v_mfma_f32_16x16x32_bf16 v[80:83], v[156:159], v[206:209], v[80:83]
	v_mfma_f32_16x16x32_bf16 v[68:71], v[148:151], v[214:217], v[68:71]
	s_setprio 3
	s_barrier
	v_mfma_f32_16x16x32_bf16 v[64:67], v[156:159], v[214:217], v[64:67]
	s_setprio 0
	s_add_i32 s63, s55, s42
	v_lshl_add_u64 v[218:219], s[6:7], 0, v[162:163]
	s_mov_b32 m0, s63
	ds_read_b128 v[178:181], v204 offset:16384
	ds_read_b128 v[182:185], v204 offset:17408
	ds_read_b128 v[186:189], v204 offset:18432
	ds_read_b128 v[190:193], v204 offset:19456
	ds_read_b128 v[194:197], v204 offset:20480
	ds_read_b128 v[206:209], v204 offset:21504
	ds_read_b128 v[210:213], v204 offset:22528
	ds_read_b128 v[214:217], v204 offset:23552
	v_lshl_add_u32 v229, s2, 8, v198
	v_lshl_or_b32 v228, s58, 8, v201
	v_lshlrev_b32_e32 v228, 1, v228
	v_lshl_add_u32 v228, v229, 11, v228
	s_add_u32 s84, s20, 0x0
	s_addc_u32 s85, s21, 0
	global_load_lds_dwordx4 v228, s[84:85]
	s_add_i32 m0, s63, 0x2000
	s_add_u32 s64, s6, 0x40000
	v_lshl_add_u64 v[220:221], s[6:7], 0, v[166:167]
	s_addc_u32 s65, s7, 0
	s_add_i32 s63, s56, s42
	s_add_u32 s84, s8, 0x0
	s_addc_u32 s85, s9, 0
	global_load_lds_dwordx4 v228, s[84:85]
	v_lshl_add_u64 v[222:223], s[64:65], 0, v[162:163]
	s_mov_b32 m0, s63
	v_lshl_add_u64 v[224:225], s[40:41], 0, v[164:165]
	s_add_u32 s84, s8, 0x100
	s_addc_u32 s85, s9, 0
	global_load_lds_dwordx4 v228, s[84:85]
	v_lshl_add_u64 v[222:223], s[64:65], 0, v[166:167]
	s_add_i32 m0, s63, 0x2000
	s_nop 0
	s_add_u32 s84, s20, 0x100
	s_addc_u32 s85, s21, 0
	global_load_lds_dwordx4 v228, s[84:85]
	v_lshl_add_u64 v[222:223], s[40:41], 0, v[160:161]
	s_mov_b32 m0, s44
	s_nop 0
	s_add_u32 s84, s8, 0x8000
	s_addc_u32 s85, s9, 0
	global_load_lds_dwordx4 v228, s[84:85]
	s_mov_b32 m0, s45
	s_nop 0
	s_add_u32 s84, s20, 0x8000
	s_addc_u32 s85, s21, 0
	global_load_lds_dwordx4 v228, s[84:85]
	s_waitcnt vmcnt(8)
	s_waitcnt lgkmcnt(0)
	s_setprio 1
	s_barrier
	s_waitcnt lgkmcnt(0)
	v_mfma_f32_16x16x32_bf16 v[60:63], v[128:131], v[178:181], v[60:63]
	v_mfma_f32_16x16x32_bf16 v[56:59], v[136:139], v[178:181], v[56:59]
	v_mfma_f32_16x16x32_bf16 v[44:47], v[128:131], v[186:189], v[44:47]
	v_mfma_f32_16x16x32_bf16 v[40:43], v[136:139], v[186:189], v[40:43]
	v_mfma_f32_16x16x32_bf16 v[28:31], v[128:131], v[194:197], v[28:31]
	v_mfma_f32_16x16x32_bf16 v[24:27], v[136:139], v[194:197], v[24:27]
	v_mfma_f32_16x16x32_bf16 v[12:15], v[128:131], v[210:213], v[12:15]
	v_mfma_f32_16x16x32_bf16 v[8:11], v[136:139], v[210:213], v[8:11]
	v_mfma_f32_16x16x32_bf16 v[60:63], v[132:135], v[182:185], v[60:63]
	v_mfma_f32_16x16x32_bf16 v[56:59], v[140:143], v[182:185], v[56:59]
	v_mfma_f32_16x16x32_bf16 v[44:47], v[132:135], v[190:193], v[44:47]
	v_mfma_f32_16x16x32_bf16 v[40:43], v[140:143], v[190:193], v[40:43]
	v_mfma_f32_16x16x32_bf16 v[28:31], v[132:135], v[206:209], v[28:31]
	v_mfma_f32_16x16x32_bf16 v[24:27], v[140:143], v[206:209], v[24:27]
	v_mfma_f32_16x16x32_bf16 v[12:15], v[132:135], v[214:217], v[12:15]
	v_mfma_f32_16x16x32_bf16 v[8:11], v[140:143], v[214:217], v[8:11]
	s_setprio 0
	s_setprio 1
	v_mfma_f32_16x16x32_bf16 v[52:55], v[144:147], v[178:181], v[52:55]
	v_mfma_f32_16x16x32_bf16 v[48:51], v[152:155], v[178:181], v[48:51]
	v_mfma_f32_16x16x32_bf16 v[36:39], v[144:147], v[186:189], v[36:39]
	v_mfma_f32_16x16x32_bf16 v[32:35], v[152:155], v[186:189], v[32:35]
	v_mfma_f32_16x16x32_bf16 v[20:23], v[144:147], v[194:197], v[20:23]
	v_mfma_f32_16x16x32_bf16 v[16:19], v[152:155], v[194:197], v[16:19]
	v_mfma_f32_16x16x32_bf16 v[4:7], v[144:147], v[210:213], v[4:7]
	v_mfma_f32_16x16x32_bf16 v[0:3], v[152:155], v[210:213], v[0:3]
	v_mfma_f32_16x16x32_bf16 v[52:55], v[148:151], v[182:185], v[52:55]
	v_mfma_f32_16x16x32_bf16 v[48:51], v[156:159], v[182:185], v[48:51]
	v_mfma_f32_16x16x32_bf16 v[36:39], v[148:151], v[190:193], v[36:39]
	v_mfma_f32_16x16x32_bf16 v[32:35], v[156:159], v[190:193], v[32:35]
	v_mfma_f32_16x16x32_bf16 v[20:23], v[148:151], v[206:209], v[20:23]
	v_mfma_f32_16x16x32_bf16 v[16:19], v[156:159], v[206:209], v[16:19]
	v_mfma_f32_16x16x32_bf16 v[4:7], v[148:151], v[214:217], v[4:7]
	s_setprio 3
	s_barrier
; #define PG8_STAGE(bufoff, gbase, voff) do { _Pragma("unroll") for (int _i = 0; _i < 2; ++_i) \
;         __builtin_amdgcn_global_load_lds((const unsigned*)((const char*)(gbase) + (voff)[_i]), (PG8_LAS unsigned*)(lds + (bufoff) + ldsw + _i * 8192), 16, 0, 0); } while (0)
; #define PG8_LDA(dst, b, h) do { _Pragma("unroll") for (int m = 0; m < 4; ++m) _Pragma("unroll") for (int k = 0; k < 2; ++k) dst[m][k] = *(const PG8_LAS bf16x8*)(lds + PG8_SA(b, h) + aoff + m * 2048 + k * 1024); } while (0)
; #define PG8_LDB(dst, b, h) do { _Pragma("unroll") for (int n = 0; n < 2; ++n) _Pragma("unroll") for (int k = 0; k < 2; ++k) dst[n][k] = *(const PG8_LAS bf16x8*)(lds + PG8_SB(b, h) + boff + n * 2048 + k * 1024); } while (0)
;     __device__ __forceinline__ void operator()(const f32x4 (&acc)[2][2][4][2], const Unit& u, int wr, int wc, int fr, int fq) const {
;     ...
;             for (int m = 0; m < 4; ++m)
; #pragma unroll
;                 for (int bj = 0; bj < 2; ++bj) { const size_t off = (size_t)(row0 + ai * HALF + m * 16) * DM + col0 + bj * HALF; prv[m][bj] = *(const u32x4*)(PR + off); xbv[m][bj] = *(const u32x4*)(Xb + off); }
; template <class Epi, class Sched, bool ALIGN_EPI = false, bool SP2 = false>
; __device__ __forceinline__ void gemm_phase(PG8_LAS unsigned char* lds, const Gemm g, const Sched& S, const Epi& E) {
;     ...
;             PG8_LDB(B0, 0, 0); PG8_LDB(B1, 0, 1); PG8_SCHED; PG8_LDA(At, 0, 0); PG8_STAGE(PG8_SA(1, 1), a1 + hstep, voffA);
;             PG8_WAIT_V(8); PG8_WAIT_L(0); PG8_BAR; PG8_MMA(0, 0, At, B0); PG8_MMA(0, 1, At, B1); PG8_BAR; PG8_SCHED;
;             PG8_LDA(At, 0, 1); PG8_STAGE(PG8_SB(0, 0), b2, voffB); PG8_STAGE(PG8_SB(0, 1), b2 + hstep, voffB); PG8_STAGE(PG8_SA(0, 0), a2, voffA);
;             PG8_WAIT_V(8); PG8_WAIT_L(0); PG8_BAR; PG8_MMA(1, 0, At, B0); PG8_MMA(1, 1, At, B1); PG8_BAR; PG8_SCHED;
;             PG8_LDB(B0, 1, 0); PG8_LDB(B1, 1, 1); PG8_SCHED; PG8_LDA(At, 1, 0); PG8_STAGE(PG8_SA(0, 1), a2 + hstep, voffA);
;             PG8_WAIT_V(8); PG8_WAIT_L(0); PG8_BAR; PG8_MMA(0, 0, At, B0); PG8_MMA(0, 1, At, B1); PG8_BAR; PG8_SCHED;
;             PG8_LDA(At, 1, 1); PG8_STAGE(PG8_SB(1, 0), b3, voffB); PG8_STAGE(PG8_SB(1, 1), b3 + hstep, voffB); PG8_STAGE(PG8_SA(1, 0), a3, voffA);
;             PG8_WAIT_V(8); PG8_WAIT_L(0); PG8_BAR; PG8_MMA(1, 0, At, B0); PG8_MMA(1, 1, At, B1); PG8_BAR; PG8_SCHED;
	v_mfma_f32_16x16x32_bf16 v[0:3], v[156:159], v[214:217], v[0:3]
	s_setprio 0
	s_add_i32 s63, 0, 0x18000
	s_add_i32 s64, 0, 0x1c000
	v_add_u32_e32 v140, s63, v199
	v_add_u32_e32 v156, s64, v199
	ds_read_b128 v[128:131], v140
	ds_read_b128 v[132:135], v140 offset:1024
	ds_read_b128 v[136:139], v140 offset:2048
	ds_read_b128 v[140:143], v140 offset:3072
	ds_read_b128 v[144:147], v156
	ds_read_b128 v[148:151], v156 offset:1024
	ds_read_b128 v[152:155], v156 offset:2048
	ds_read_b128 v[156:159], v156 offset:3072
	s_add_u32 s40, s40, 0x40000
	s_addc_u32 s41, s41, 0
	s_mov_b32 m0, s46
	v_lshl_add_u64 v[226:227], s[40:41], 0, v[160:161]
	ds_read_b128 v[178:181], v204 offset:32768
	ds_read_b128 v[182:185], v204 offset:33792
	ds_read_b128 v[186:189], v204 offset:34816
	ds_read_b128 v[190:193], v204 offset:35840
	ds_read_b128 v[194:197], v204 offset:36864
	ds_read_b128 v[206:209], v204 offset:37888
	ds_read_b128 v[210:213], v204 offset:38912
	ds_read_b128 v[214:217], v204 offset:39936
	s_add_u32 s84, s8, 0x10000
	s_addc_u32 s85, s9, 0
	global_load_lds_dwordx4 v228, s[84:85]
	v_lshl_add_u64 v[226:227], s[40:41], 0, v[164:165]
	s_mov_b32 m0, s47
	s_nop 0
	s_add_u32 s84, s20, 0x10000
	s_addc_u32 s85, s21, 0
	global_load_lds_dwordx4 v228, s[84:85]
	s_waitcnt vmcnt(8)
	s_waitcnt lgkmcnt(0)
	s_setprio 1
	s_barrier
	s_waitcnt lgkmcnt(0)
	v_mfma_f32_16x16x32_bf16 v[124:127], v[128:131], v[178:181], v[124:127]
	v_mfma_f32_16x16x32_bf16 v[120:123], v[136:139], v[178:181], v[120:123]
	v_mfma_f32_16x16x32_bf16 v[108:111], v[128:131], v[186:189], v[108:111]
	v_mfma_f32_16x16x32_bf16 v[104:107], v[136:139], v[186:189], v[104:107]
	v_mfma_f32_16x16x32_bf16 v[92:95], v[128:131], v[194:197], v[92:95]
	v_mfma_f32_16x16x32_bf16 v[88:91], v[136:139], v[194:197], v[88:91]
	v_mfma_f32_16x16x32_bf16 v[76:79], v[128:131], v[210:213], v[76:79]
	v_mfma_f32_16x16x32_bf16 v[72:75], v[136:139], v[210:213], v[72:75]
	v_mfma_f32_16x16x32_bf16 v[124:127], v[132:135], v[182:185], v[124:127]
	v_mfma_f32_16x16x32_bf16 v[120:123], v[140:143], v[182:185], v[120:123]
	v_mfma_f32_16x16x32_bf16 v[108:111], v[132:135], v[190:193], v[108:111]
	v_mfma_f32_16x16x32_bf16 v[104:107], v[140:143], v[190:193], v[104:107]
	v_mfma_f32_16x16x32_bf16 v[92:95], v[132:135], v[206:209], v[92:95]
	v_mfma_f32_16x16x32_bf16 v[88:91], v[140:143], v[206:209], v[88:91]
	v_mfma_f32_16x16x32_bf16 v[76:79], v[132:135], v[214:217], v[76:79]
	v_mfma_f32_16x16x32_bf16 v[72:75], v[140:143], v[214:217], v[72:75]
	s_setprio 0
	s_setprio 1
	v_mfma_f32_16x16x32_bf16 v[116:119], v[144:147], v[178:181], v[116:119]
	v_mfma_f32_16x16x32_bf16 v[112:115], v[152:155], v[178:181], v[112:115]
	v_mfma_f32_16x16x32_bf16 v[100:103], v[144:147], v[186:189], v[100:103]
	v_mfma_f32_16x16x32_bf16 v[96:99], v[152:155], v[186:189], v[96:99]
	v_mfma_f32_16x16x32_bf16 v[84:87], v[144:147], v[194:197], v[84:87]
	v_mfma_f32_16x16x32_bf16 v[80:83], v[152:155], v[194:197], v[80:83]
	v_mfma_f32_16x16x32_bf16 v[68:71], v[144:147], v[210:213], v[68:71]
	v_mfma_f32_16x16x32_bf16 v[64:67], v[152:155], v[210:213], v[64:67]
	v_mfma_f32_16x16x32_bf16 v[116:119], v[148:151], v[182:185], v[116:119]
	v_mfma_f32_16x16x32_bf16 v[112:115], v[156:159], v[182:185], v[112:115]
	v_mfma_f32_16x16x32_bf16 v[100:103], v[148:151], v[190:193], v[100:103]
	v_mfma_f32_16x16x32_bf16 v[96:99], v[156:159], v[190:193], v[96:99]
	v_mfma_f32_16x16x32_bf16 v[84:87], v[148:151], v[206:209], v[84:87]
	v_mfma_f32_16x16x32_bf16 v[80:83], v[156:159], v[206:209], v[80:83]
	v_mfma_f32_16x16x32_bf16 v[68:71], v[148:151], v[214:217], v[68:71]
	s_setprio 3
	s_barrier
	v_mfma_f32_16x16x32_bf16 v[64:67], v[156:159], v[214:217], v[64:67]
	s_setprio 0
	s_add_i32 s40, s63, s42
	v_lshl_add_u64 v[218:219], v[218:219], 0, s[12:13]
	s_mov_b32 m0, s40
	ds_read_b128 v[178:181], v204 offset:49152
	ds_read_b128 v[182:185], v204 offset:50176
	ds_read_b128 v[186:189], v204 offset:51200
	ds_read_b128 v[190:193], v204 offset:52224
	ds_read_b128 v[194:197], v204 offset:53248
	ds_read_b128 v[206:209], v204 offset:54272
	ds_read_b128 v[210:213], v204 offset:55296
	ds_read_b128 v[214:217], v204 offset:56320
	s_add_u32 s84, s8, 0x18000
	s_addc_u32 s85, s9, 0
	global_load_lds_dwordx4 v228, s[84:85]
	s_add_i32 m0, s40, 0x2000
	s_add_u32 s6, s6, 0x40080
	v_lshl_add_u64 v[218:219], v[220:221], 0, s[12:13]
	s_addc_u32 s7, s7, 0
	s_add_i32 s40, s64, s42
	s_add_u32 s84, s20, 0x18000
	s_addc_u32 s85, s21, 0
	global_load_lds_dwordx4 v228, s[84:85]
	v_lshl_add_u64 v[218:219], s[6:7], 0, v[162:163]
	s_mov_b32 m0, s40
	s_nop 0
	s_add_u32 s84, s8, 0x8100
	s_addc_u32 s85, s9, 0
	global_load_lds_dwordx4 v228, s[84:85]
	v_lshl_add_u64 v[218:219], s[6:7], 0, v[166:167]
	s_add_i32 m0, s40, 0x2000
	s_nop 0
	s_add_u32 s84, s20, 0x8100
	s_addc_u32 s85, s21, 0
	global_load_lds_dwordx4 v228, s[84:85]
	v_lshl_add_u64 v[218:219], v[222:223], 0, s[12:13]
	s_mov_b32 m0, s52
	s_nop 0
	s_add_u32 s84, s8, 0x10100
	s_addc_u32 s85, s9, 0
	global_load_lds_dwordx4 v228, s[84:85]
	v_lshl_add_u64 v[218:219], v[224:225], 0, s[12:13]
	s_mov_b32 m0, s53
	s_nop 0
	s_add_u32 s84, s20, 0x10100
	s_addc_u32 s85, s21, 0
	global_load_lds_dwordx4 v228, s[84:85]
	s_waitcnt vmcnt(8)
	s_waitcnt lgkmcnt(0)
	s_setprio 1
	s_barrier
; #define PG8_STAGE(bufoff, gbase, voff) do { _Pragma("unroll") for (int _i = 0; _i < 2; ++_i) \
;         __builtin_amdgcn_global_load_lds((const unsigned*)((const char*)(gbase) + (voff)[_i]), (PG8_LAS unsigned*)(lds + (bufoff) + ldsw + _i * 8192), 16, 0, 0); } while (0)
; #define PG8_LDA(dst, b, h) do { _Pragma("unroll") for (int m = 0; m < 4; ++m) _Pragma("unroll") for (int k = 0; k < 2; ++k) dst[m][k] = *(const PG8_LAS bf16x8*)(lds + PG8_SA(b, h) + aoff + m * 2048 + k * 1024); } while (0)
; #define PG8_MMA(ai, bj, At, Bt) do { __builtin_amdgcn_s_setprio(1); _Pragma("unroll") for (int m = 0; m < 4; ++m) _Pragma("unroll") for (int n = 0; n < 2; ++n) _Pragma("unroll") for (int k = 0; k < 2; ++k) \
;         acc[ai][bj][m][n] = __builtin_amdgcn_mfma_f32_16x16x32_bf16(Bt[n][k], At[m][k], acc[ai][bj][m][n], 0, 0, 0); __builtin_amdgcn_s_setprio(0); } while (0)
; #define PG8_WAIT_V(n) asm volatile("s_waitcnt vmcnt(" #n ")" ::: "memory")
; #define PG8_WAIT_L(n) asm volatile("s_waitcnt lgkmcnt(" #n ")" ::: "memory")
; #define PG8_BAR __builtin_amdgcn_s_barrier()
; #define PG8_SCHED __builtin_amdgcn_sched_barrier(0)
; template <class Epi, class Sched, bool ALIGN_EPI = false, bool SP2 = false>
; __device__ __forceinline__ void gemm_phase(PG8_LAS unsigned char* lds, const Gemm g, const Sched& S, const Epi& E) {
;     ...
;             PG8_WAIT_V(8); PG8_WAIT_L(0); PG8_BAR; PG8_MMA(0, 0, At, B0); PG8_MMA(0, 1, At, B1); PG8_BAR; PG8_SCHED;
;             PG8_LDA(At, 1, 1); PG8_STAGE(PG8_SB(1, 0), b3, voffB); PG8_STAGE(PG8_SB(1, 1), b3 + hstep, voffB); PG8_STAGE(PG8_SA(1, 0), a3, voffA);
;             PG8_WAIT_V(8); PG8_WAIT_L(0); PG8_BAR; PG8_MMA(1, 0, At, B0); PG8_MMA(1, 1, At, B1); PG8_BAR; PG8_SCHED;
;     ...
;         if constexpr (ALIGN_EPI) { if (wr == 0) PG8_BAR; }
	s_waitcnt lgkmcnt(0)
	v_mfma_f32_16x16x32_bf16 v[60:63], v[128:131], v[178:181], v[60:63]
	v_mfma_f32_16x16x32_bf16 v[56:59], v[136:139], v[178:181], v[56:59]
	v_mfma_f32_16x16x32_bf16 v[44:47], v[128:131], v[186:189], v[44:47]
	v_mfma_f32_16x16x32_bf16 v[40:43], v[136:139], v[186:189], v[40:43]
	v_mfma_f32_16x16x32_bf16 v[28:31], v[128:131], v[194:197], v[28:31]
	v_mfma_f32_16x16x32_bf16 v[24:27], v[136:139], v[194:197], v[24:27]
	v_mfma_f32_16x16x32_bf16 v[12:15], v[128:131], v[210:213], v[12:15]
	v_mfma_f32_16x16x32_bf16 v[8:11], v[136:139], v[210:213], v[8:11]
	v_mfma_f32_16x16x32_bf16 v[60:63], v[132:135], v[182:185], v[60:63]
	v_mfma_f32_16x16x32_bf16 v[56:59], v[140:143], v[182:185], v[56:59]
	v_mfma_f32_16x16x32_bf16 v[44:47], v[132:135], v[190:193], v[44:47]
	v_mfma_f32_16x16x32_bf16 v[40:43], v[140:143], v[190:193], v[40:43]
	v_mfma_f32_16x16x32_bf16 v[28:31], v[132:135], v[206:209], v[28:31]
	v_mfma_f32_16x16x32_bf16 v[24:27], v[140:143], v[206:209], v[24:27]
	v_mfma_f32_16x16x32_bf16 v[12:15], v[132:135], v[214:217], v[12:15]
	v_mfma_f32_16x16x32_bf16 v[8:11], v[140:143], v[214:217], v[8:11]
	s_setprio 0
	s_setprio 1
	v_mfma_f32_16x16x32_bf16 v[52:55], v[144:147], v[178:181], v[52:55]
	v_mfma_f32_16x16x32_bf16 v[48:51], v[152:155], v[178:181], v[48:51]
	v_mfma_f32_16x16x32_bf16 v[36:39], v[144:147], v[186:189], v[36:39]
	v_mfma_f32_16x16x32_bf16 v[32:35], v[152:155], v[186:189], v[32:35]
	v_mfma_f32_16x16x32_bf16 v[20:23], v[144:147], v[194:197], v[20:23]
	v_mfma_f32_16x16x32_bf16 v[16:19], v[152:155], v[194:197], v[16:19]
	v_mfma_f32_16x16x32_bf16 v[4:7], v[144:147], v[210:213], v[4:7]
	v_mfma_f32_16x16x32_bf16 v[0:3], v[152:155], v[210:213], v[0:3]
	v_mfma_f32_16x16x32_bf16 v[52:55], v[148:151], v[182:185], v[52:55]
	v_mfma_f32_16x16x32_bf16 v[48:51], v[156:159], v[182:185], v[48:51]
	v_mfma_f32_16x16x32_bf16 v[36:39], v[148:151], v[190:193], v[36:39]
	v_mfma_f32_16x16x32_bf16 v[32:35], v[156:159], v[190:193], v[32:35]
	v_mfma_f32_16x16x32_bf16 v[20:23], v[148:151], v[206:209], v[20:23]
	v_mfma_f32_16x16x32_bf16 v[16:19], v[156:159], v[206:209], v[16:19]
	v_mfma_f32_16x16x32_bf16 v[4:7], v[148:151], v[214:217], v[4:7]
	s_setprio 3
	s_barrier
	v_mfma_f32_16x16x32_bf16 v[0:3], v[156:159], v[214:217], v[0:3]
	s_setprio 0
	s_add_i32 s62, s62, 2
	s_add_u32 s4, s4, 0x100
	s_addc_u32 s5, s5, 0
	s_add_u32 s60, s60, 0x100
	s_addc_u32 s61, s61, 0
	s_mov_b32 s32, 1
	s_branch .Lp6x_done
.Lp6x_gen:
	s_mov_b32 s32, 0
.Lp6x_done:
	s_and_b64 vcc, exec, s[14:15]
	s_cbranch_vccz .LBB0_1036
	s_barrier
; __device__ __forceinline__ void row_rstd8(const float* SS, int row0, int fq, float (&rs)[2][4]) {
; #pragma unroll
;     for (int ai = 0; ai < 2; ++ai)
; #pragma unroll
;         for (int m = 0; m < 4; ++m) { const f32x4 t = *(const f32x4*)(SS + (size_t)(row0 + ai * HALF + m * 16) * 16 + 4 * fq); rs[ai][m] = (t[0] + t[1]) + (t[2] + t[3]); }
; #pragma unroll
;     for (int ai = 0; ai < 2; ++ai)
; #pragma unroll
;         for (int m = 0; m < 4; ++m) { float v = sum_fq(rs[ai][m]); rs[ai][m] = rsqrtf(v * (1.f / DM) + EPS); }
; }
;     __device__ __forceinline__ void operator()(const f32x4 (&acc)[2][2][4][2], const Unit& u, int wr, int wc, int fr, int fq) const {
;     ...
;         if (u.pm == rtab_pm) {
; #pragma unroll
;             for (int ai = 0; ai < 2; ++ai)
; #pragma unroll
;                 for (int m = 0; m < 4; ++m) rs[ai][m] = rtab[wr * 64 + fr + ai * HALF + m * 16];
;         } else row_rstd8(SS, row0, fq, rs);
.LBB0_1036:
	v_lshl_add_u32 v134, s2, 8, v198
	v_or_b32_e32 v132, 16, v134
	v_or_b32_e32 v130, 32, v134
	v_or_b32_e32 v128, 48, v134
	s_cmp_lg_u32 s2, s17
	v_ashrrev_i32_e32 v133, 31, v132
	s_mov_b64 s[2:3], -1
	v_ashrrev_i32_e32 v135, 31, v134
	v_ashrrev_i32_e32 v131, 31, v130
	v_ashrrev_i32_e32 v129, 31, v128
	v_add_u32_e32 v136, 0x80, v134
	s_cbranch_scc0 .LBB0_1038
	v_lshlrev_b64 v[138:139], 6, v[134:135]
	v_lshlrev_b64 v[142:143], 6, v[132:133]
	v_lshl_add_u64 v[154:155], v[168:169], 0, v[138:139]
	v_lshl_add_u64 v[142:143], v[168:169], 0, v[142:143]
	v_lshlrev_b64 v[146:147], 6, v[130:131]
	global_load_dwordx4 v[138:141], v[154:155], off
	v_lshl_add_u64 v[146:147], v[168:169], 0, v[146:147]
	global_load_dwordx4 v[142:145], v[142:143], off
	v_lshlrev_b64 v[150:151], 6, v[128:129]
	global_load_dwordx4 v[146:149], v[146:147], off
	v_lshl_add_u64 v[150:151], v[168:169], 0, v[150:151]
	global_load_dwordx4 v[150:153], v[150:151], off
	v_add_u32_e32 v182, 0x80, v134
	v_ashrrev_i32_e32 v183, 31, v182
	v_add_co_u32_e32 v158, vcc, s48, v154
	v_lshlrev_b64 v[184:185], 6, v[182:183]
	s_nop 0
	v_addc_co_u32_e32 v159, vcc, 0, v155, vcc
	v_lshl_add_u64 v[184:185], v[168:169], 0, v[184:185]
	global_load_dwordx4 v[154:157], v[158:159], off offset:2048
	global_load_dwordx4 v[178:181], v[158:159], off offset:3072
	s_nop 0
	global_load_dwordx4 v[184:187], v[184:185], off
	s_nop 0
	global_load_dwordx4 v[188:191], v[158:159], off offset:1024
	v_mov_b64_e32 v[158:159], s[18:19]
	s_waitcnt vmcnt(0)
	v_mov_b32_e32 v192, v139
	v_mov_b32_e32 v193, v140
	v_mov_b32_e32 v139, v141
	v_mov_b32_e32 v140, v143
	v_mov_b32_e32 v141, v144
	v_mov_b32_e32 v143, v145
	v_mov_b32_e32 v144, v147
	v_mov_b32_e32 v145, v148
	v_mov_b32_e32 v147, v149
	v_pk_add_f32 v[138:139], v[192:193], v[138:139]
	v_pk_add_f32 v[140:141], v[140:141], v[142:143]
	v_pk_add_f32 v[142:143], v[144:145], v[146:147]
	v_pk_add_f32 v[138:139], v[138:139], v[138:139] op_sel:[0,1] op_sel_hi:[1,0]
	v_pk_add_f32 v[140:141], v[140:141], v[140:141] op_sel:[0,1] op_sel_hi:[1,0]
	v_pk_add_f32 v[142:143], v[142:143], v[142:143] op_sel:[0,1] op_sel_hi:[1,0]
	v_mov_b32_e32 v137, v138
	v_mov_b32_e32 v141, v140
	v_mov_b32_e32 v143, v142
	v_permlane32_swap_b32_e32 v138, v137
	v_permlane32_swap_b32_e32 v140, v141
	v_permlane32_swap_b32_e32 v142, v143
	v_add_f32_e32 v139, v138, v137
	v_add_f32_e32 v138, v140, v141
	v_add_f32_e32 v141, v142, v143
	v_mov_b32_e32 v143, v139
	v_mov_b32_e32 v142, v138
	s_nop 0
	v_permlane16_swap_b32_e32 v139, v143
	v_permlane16_swap_b32_e32 v138, v142
	v_pk_add_f32 v[138:139], v[138:139], v[142:143]
	v_mov_b32_e32 v148, v151
	v_mov_b32_e32 v149, v152
	v_mov_b32_e32 v151, v153
	v_pk_fma_f32 v[138:139], v[138:139], s[16:17], v[158:159] op_sel_hi:[1,0,0]
	v_pk_add_f32 v[144:145], v[148:149], v[150:151]
	v_mul_f32_e32 v137, 0x4b800000, v139
	v_cmp_gt_f32_e32 vcc, s57, v139
	v_pk_add_f32 v[144:145], v[144:145], v[144:145] op_sel:[0,1] op_sel_hi:[1,0]
	v_mul_f32_e32 v140, 0x4b800000, v138
	v_cndmask_b32_e32 v137, v139, v137, vcc
	v_rsq_f32_e32 v139, v137
	v_mov_b32_e32 v137, v144
	v_cmp_gt_f32_e64 s[2:3], s57, v138
	s_nop 0
	v_permlane32_swap_b32_e32 v144, v137
	v_cndmask_b32_e64 v138, v138, v140, s[2:3]
	v_add_f32_e32 v140, v144, v137
	v_mov_b32_e32 v145, v141
	v_mov_b32_e32 v144, v140
	s_nop 0
	v_permlane16_swap_b32_e32 v141, v145
	v_permlane16_swap_b32_e32 v140, v144
	v_pk_add_f32 v[140:141], v[140:141], v[144:145]
	v_rsq_f32_e32 v138, v138
	v_pk_fma_f32 v[140:141], v[140:141], s[16:17], v[158:159] op_sel_hi:[1,0,0]
	v_mov_b32_e32 v150, v185
	v_mul_f32_e32 v137, 0x4b800000, v141
	v_cmp_gt_f32_e64 s[4:5], s57, v141
	v_cmp_gt_f32_e64 s[6:7], s57, v140
	v_mov_b32_e32 v151, v186
	v_cndmask_b32_e64 v137, v141, v137, s[4:5]
	v_rsq_f32_e32 v141, v137
	v_mul_f32_e32 v137, 0x4b800000, v140
	v_cndmask_b32_e64 v137, v140, v137, s[6:7]
	v_mov_b32_e32 v185, v187
	v_rsq_f32_e32 v140, v137
	v_pk_add_f32 v[150:151], v[150:151], v[184:185]
	v_mov_b32_e32 v152, v189
	v_mov_b32_e32 v153, v190
	v_mov_b32_e32 v189, v191
	v_pk_add_f32 v[150:151], v[150:151], v[150:151] op_sel:[0,1] op_sel_hi:[1,0]
	v_pk_add_f32 v[152:153], v[152:153], v[188:189]
	v_pk_mul_f32 v[142:143], v[138:139], s[22:23] op_sel_hi:[1,0]
	v_mov_b32_e32 v137, v150
	v_pk_add_f32 v[152:153], v[152:153], v[152:153] op_sel:[0,1] op_sel_hi:[1,0]
	v_cndmask_b32_e64 v195, v138, v142, s[2:3]
	v_cndmask_b32_e32 v194, v139, v143, vcc
	v_pk_mul_f32 v[138:139], v[140:141], s[22:23] op_sel_hi:[1,0]
	v_permlane32_swap_b32_e32 v150, v137
	v_cndmask_b32_e64 v188, v141, v139, s[4:5]
	v_add_f32_e32 v139, v150, v137
	v_mov_b32_e32 v137, v152
	s_nop 1
	v_permlane32_swap_b32_e32 v152, v137
	v_cndmask_b32_e64 v189, v140, v138, s[6:7]
	v_add_f32_e32 v138, v152, v137
	v_mov_b32_e32 v141, v139
	v_mov_b32_e32 v140, v138
	s_nop 0
	v_permlane16_swap_b32_e32 v139, v141
	v_permlane16_swap_b32_e32 v138, v140
	v_pk_add_f32 v[138:139], v[138:139], v[140:141]
	v_mov_b32_e32 v146, v155
	v_pk_fma_f32 v[138:139], v[138:139], s[16:17], v[158:159] op_sel_hi:[1,0,0]
	v_mov_b32_e32 v147, v156
	v_mul_f32_e32 v137, 0x4b800000, v139
	v_cmp_gt_f32_e32 vcc, s57, v139
	v_mov_b32_e32 v155, v157
	v_pk_add_f32 v[146:147], v[146:147], v[154:155]
	v_cndmask_b32_e32 v137, v139, v137, vcc
	v_rsq_f32_e32 v139, v137
	v_mul_f32_e32 v137, 0x4b800000, v138
	v_cmp_gt_f32_e64 s[2:3], s57, v138
	v_mov_b32_e32 v148, v179
	v_mov_b32_e32 v149, v180
	v_mov_b32_e32 v179, v181
	v_pk_add_f32 v[146:147], v[146:147], v[146:147] op_sel:[0,1] op_sel_hi:[1,0]
	v_cndmask_b32_e64 v137, v138, v137, s[2:3]
	v_pk_add_f32 v[148:149], v[148:149], v[178:179]
	v_rsq_f32_e32 v138, v137
	v_mov_b32_e32 v137, v146
	v_pk_add_f32 v[148:149], v[148:149], v[148:149] op_sel:[0,1] op_sel_hi:[1,0]
	s_nop 0
	v_permlane32_swap_b32_e32 v146, v137
	v_add_f32_e32 v141, v146, v137
	v_mov_b32_e32 v137, v148
	s_nop 1
	v_permlane32_swap_b32_e32 v148, v137
	v_add_f32_e32 v140, v148, v137
	v_mov_b32_e32 v143, v141
	v_mov_b32_e32 v142, v140
	s_nop 0
	v_permlane16_swap_b32_e32 v141, v143
	v_permlane16_swap_b32_e32 v140, v142
	v_pk_add_f32 v[140:141], v[140:141], v[142:143]
	v_pk_mul_f32 v[142:143], v[138:139], s[22:23] op_sel_hi:[1,0]
	v_pk_fma_f32 v[140:141], v[140:141], s[16:17], v[158:159] op_sel_hi:[1,0,0]
	v_cndmask_b32_e64 v181, v138, v142, s[2:3]
	v_mul_f32_e32 v137, 0x4b800000, v141
	v_cmp_gt_f32_e64 s[4:5], s57, v141
	v_cmp_gt_f32_e64 s[6:7], s57, v140
	v_cndmask_b32_e32 v180, v139, v143, vcc
	v_cndmask_b32_e64 v137, v141, v137, s[4:5]
	v_rsq_f32_e32 v141, v137
	v_mul_f32_e32 v137, 0x4b800000, v140
	v_cndmask_b32_e64 v137, v140, v137, s[6:7]
	v_rsq_f32_e32 v140, v137
	s_mov_b64 s[2:3], 0
	v_mov_b64_e32 v[184:185], v[182:183]
	v_pk_mul_f32 v[138:139], v[140:141], s[22:23] op_sel_hi:[1,0]
	s_nop 0
	v_cndmask_b32_e64 v179, v140, v138, s[6:7]
	v_cndmask_b32_e64 v178, v141, v139, s[4:5]

;     __device__ __forceinline__ void operator()(const f32x4 (&acc)[2][2][4][2], const Unit& u, int wr, int wc, int fr, int fq) const {
;     ...
;             u32x4 prv[4][2], xbv[4][2];
; #pragma unroll
;             for (int m = 0; m < 4; ++m)
; #pragma unroll
;                 for (int bj = 0; bj < 2; ++bj) { const size_t off = (size_t)(row0 + ai * HALF + m * 16) * DM + col0 + bj * HALF; prv[m][bj] = *(const u32x4*)(PR + off); xbv[m][bj] = *(const u32x4*)(Xb + off); }
; #pragma unroll
;             for (int m = 0; m < 4; ++m) { const int row = row0 + ai * HALF + m * 16; const float r = rs[ai][m];
; #pragma unroll
;                 for (int bj = 0; bj < 2; ++bj) { const size_t off = (size_t)row * DM + col0 + bj * HALF;
;                     const u32x4 pr = prv[m][bj], xb = xbv[m][bj];
;                     const float rl = -LOG2E * r;
;                     const f32x4 t0 = acc[ai][bj][m][0] * rl, t1 = acc[ai][bj][m][1] * rl;
;                     const f32x4 d0 = (f32x4){__builtin_amdgcn_exp2f(t0[0]), __builtin_amdgcn_exp2f(t0[1]), __builtin_amdgcn_exp2f(t0[2]), __builtin_amdgcn_exp2f(t0[3])} + 1.f;
;                     const f32x4 d1 = (f32x4){__builtin_amdgcn_exp2f(t1[0]), __builtin_amdgcn_exp2f(t1[1]), __builtin_amdgcn_exp2f(t1[2]), __builtin_amdgcn_exp2f(t1[3])} + 1.f;
;                     const f32x4 s0 = (f32x4){__builtin_amdgcn_rcpf(d0[0]), __builtin_amdgcn_rcpf(d0[1]), __builtin_amdgcn_rcpf(d0[2]), __builtin_amdgcn_rcpf(d0[3])}, s1 = (f32x4){__builtin_amdgcn_rcpf(d1[0]), __builtin_amdgcn_rcpf(d1[1]), __builtin_amdgcn_rcpf(d1[2]), __builtin_amdgcn_rcpf(d1[3])};
.LBB0_1040:
	s_cmp_lg_u32 s32, 0
	s_cbranch_scc1 .Lp6x_fast
	v_lshl_or_b32 v186, s58, 8, v201
	v_ashrrev_i32_e32 v187, 31, v186
	v_lshlrev_b64 v[134:135], 10, v[134:135]
	v_lshl_add_u64 v[230:231], v[134:135], 0, v[186:187]
	v_lshlrev_b64 v[134:135], 1, v[230:231]
	v_lshl_add_u64 v[136:137], s[20:21], 0, v[134:135]
	global_load_dwordx4 v[206:209], v[136:137], off
	v_lshl_add_u64 v[136:137], s[8:9], 0, v[134:135]
	global_load_dwordx4 v[210:213], v[136:137], off
	v_or_b32_e32 v134, 0x100, v134
	v_lshl_add_u64 v[138:139], s[8:9], 0, v[134:135]
	v_lshl_add_u64 v[134:135], s[20:21], 0, v[134:135]
	global_load_dwordx4 v[214:217], v[138:139], off
	global_load_dwordx4 v[218:221], v[134:135], off
	v_lshlrev_b64 v[132:133], 10, v[132:133]
	s_waitcnt lgkmcnt(0)
	v_mul_f32_e32 v194, 0xbfb8aa3b, v194
	v_pk_mul_f32 v[120:121], v[120:121], v[194:195] op_sel_hi:[1,0]
	v_lshl_add_u64 v[196:197], v[132:133], 0, v[186:187]
	v_pk_mul_f32 v[126:127], v[126:127], v[194:195] op_sel_hi:[1,0]
	v_exp_f32_e32 v236, v120
	v_exp_f32_e32 v237, v121
	v_lshlrev_b64 v[120:121], 1, v[196:197]
	v_lshlrev_b64 v[128:129], 10, v[128:129]
	v_exp_f32_e32 v234, v126
	v_exp_f32_e32 v235, v127
	v_lshl_add_u64 v[126:127], s[8:9], 0, v[120:121]
	v_lshl_add_u64 v[190:191], v[128:129], 0, v[186:187]
	v_lshl_add_u64 v[128:129], s[20:21], 0, v[120:121]
	global_load_dwordx4 v[222:225], v[126:127], off
	global_load_dwordx4 v[226:229], v[128:129], off
	v_lshlrev_b64 v[130:131], 10, v[130:131]
	v_pk_mul_f32 v[124:125], v[124:125], v[194:195] op_sel_hi:[1,0]
	v_pk_mul_f32 v[122:123], v[122:123], v[194:195] op_sel_hi:[1,0]
	v_lshl_add_u64 v[192:193], v[130:131], 0, v[186:187]
	v_exp_f32_e32 v232, v124
	v_exp_f32_e32 v233, v125
	v_exp_f32_e32 v238, v122
	v_exp_f32_e32 v239, v123
	v_lshlrev_b64 v[122:123], 1, v[192:193]
	v_lshlrev_b64 v[124:125], 1, v[190:191]
	v_or_b32_e32 v120, 0x100, v120
	v_lshl_add_u64 v[130:131], s[8:9], 0, v[122:123]
	v_lshl_add_u64 v[132:133], s[20:21], 0, v[122:123]
	v_or_b32_e32 v122, 0x100, v122
	v_lshl_add_u64 v[136:137], s[8:9], 0, v[124:125]
	v_lshl_add_u64 v[134:135], s[20:21], 0, v[124:125]
	v_or_b32_e32 v124, 0x100, v124
	v_lshl_add_u64 v[126:127], s[8:9], 0, v[120:121]
	v_lshl_add_u64 v[120:121], s[20:21], 0, v[120:121]
	v_lshl_add_u64 v[138:139], s[8:9], 0, v[122:123]
	v_lshl_add_u64 v[122:123], s[20:21], 0, v[122:123]
	v_lshl_add_u64 v[240:241], s[8:9], 0, v[124:125]
	v_lshl_add_u64 v[124:125], s[20:21], 0, v[124:125]
	global_load_dwordx4 v[144:147], v[130:131], off
	global_load_dwordx4 v[148:151], v[132:133], off
	s_nop 0
	global_load_dwordx4 v[128:131], v[136:137], off
	s_nop 0
	global_load_dwordx4 v[132:135], v[134:135], off
	s_nop 0
	global_load_dwordx4 v[152:155], v[126:127], off
	global_load_dwordx4 v[156:159], v[120:121], off
	s_nop 0
	global_load_dwordx4 v[136:139], v[138:139], off
	s_nop 0
	global_load_dwordx4 v[140:143], v[122:123], off
	s_nop 0
	global_load_dwordx4 v[120:123], v[240:241], off
	s_nop 0
	global_load_dwordx4 v[124:127], v[124:125], off
	v_pk_mul_f32 v[118:119], v[118:119], v[194:195] op_sel_hi:[1,0]
	v_pk_mul_f32 v[116:117], v[116:117], v[194:195] op_sel_hi:[1,0]
	v_pk_add_f32 v[234:235], v[234:235], 1.0 op_sel_hi:[1,0]
	v_pk_add_f32 v[232:233], v[232:233], 1.0 op_sel_hi:[1,0]
	v_pk_mul_f32 v[114:115], v[114:115], v[194:195] op_sel_hi:[1,0]
	v_pk_mul_f32 v[112:113], v[112:113], v[194:195] op_sel_hi:[1,0]
	v_exp_f32_e32 v116, v116
	v_exp_f32_e32 v117, v117
	v_exp_f32_e32 v118, v118
	v_exp_f32_e32 v119, v119
	v_pk_add_f32 v[238:239], v[238:239], 1.0 op_sel_hi:[1,0]
	v_pk_add_f32 v[236:237], v[236:237], 1.0 op_sel_hi:[1,0]
	v_rcp_f32_e32 v232, v232
	v_rcp_f32_e32 v233, v233
	v_rcp_f32_e32 v234, v234
	v_rcp_f32_e32 v235, v235
	v_exp_f32_e32 v112, v112
	v_exp_f32_e32 v114, v114
	v_exp_f32_e32 v115, v115
	v_exp_f32_e32 v113, v113
	v_rcp_f32_e32 v236, v236
	v_rcp_f32_e32 v237, v237
	v_rcp_f32_e32 v238, v238
	v_rcp_f32_e32 v239, v239
	v_pk_add_f32 v[118:119], v[118:119], 1.0 op_sel_hi:[1,0]
	v_pk_add_f32 v[116:117], v[116:117], 1.0 op_sel_hi:[1,0]
	v_lshl_add_u64 v[230:231], v[230:231], 2, s[50:51]
	v_pk_add_f32 v[114:115], v[114:115], 1.0 op_sel_hi:[1,0]
	v_pk_add_f32 v[112:113], v[112:113], 1.0 op_sel_hi:[1,0]
	v_rcp_f32_e32 v116, v116
	v_rcp_f32_e32 v117, v117
	v_rcp_f32_e32 v118, v118
	s_waitcnt vmcnt(0)
	s_branch .Lp6x_join
;     __device__ __forceinline__ void operator()(const f32x4 (&acc)[2][2][4][2], const Unit& u, int wr, int wc, int fr, int fq) const {
;     ...
;             u32x4 prv[4][2], xbv[4][2];
; #pragma unroll
;             for (int m = 0; m < 4; ++m)
; #pragma unroll
;                 for (int bj = 0; bj < 2; ++bj) { const size_t off = (size_t)(row0 + ai * HALF + m * 16) * DM + col0 + bj * HALF; prv[m][bj] = *(const u32x4*)(PR + off); xbv[m][bj] = *(const u32x4*)(Xb + off); }
; #pragma unroll
;             for (int m = 0; m < 4; ++m) { const int row = row0 + ai * HALF + m * 16; const float r = rs[ai][m];
; #pragma unroll
;                 for (int bj = 0; bj < 2; ++bj) { const size_t off = (size_t)row * DM + col0 + bj * HALF;
;                     const u32x4 pr = prv[m][bj], xb = xbv[m][bj];
;                     const float rl = -LOG2E * r;
;                     const f32x4 t0 = acc[ai][bj][m][0] * rl, t1 = acc[ai][bj][m][1] * rl;
;                     const f32x4 d0 = (f32x4){__builtin_amdgcn_exp2f(t0[0]), __builtin_amdgcn_exp2f(t0[1]), __builtin_amdgcn_exp2f(t0[2]), __builtin_amdgcn_exp2f(t0[3])} + 1.f;
;                     const f32x4 d1 = (f32x4){__builtin_amdgcn_exp2f(t1[0]), __builtin_amdgcn_exp2f(t1[1]), __builtin_amdgcn_exp2f(t1[2]), __builtin_amdgcn_exp2f(t1[3])} + 1.f;
;                     const f32x4 s0 = (f32x4){__builtin_amdgcn_rcpf(d0[0]), __builtin_amdgcn_rcpf(d0[1]), __builtin_amdgcn_rcpf(d0[2]), __builtin_amdgcn_rcpf(d0[3])}, s1 = (f32x4){__builtin_amdgcn_rcpf(d1[0]), __builtin_amdgcn_rcpf(d1[1]), __builtin_amdgcn_rcpf(d1[2]), __builtin_amdgcn_rcpf(d1[3])};
.Lp6x_fast:
	s_waitcnt vmcnt(0)
	v_mbcnt_lo_u32_b32 v252, -1, 0
	v_mbcnt_hi_u32_b32 v252, -1, v252
	v_lshlrev_b32_e32 v252, 4, v252
	v_add_u32_e32 v253, s42, v252
	v_lshl_or_b32 v186, s58, 8, v201
	v_ashrrev_i32_e32 v187, 31, v186
	v_lshlrev_b64 v[134:135], 10, v[134:135]
	v_lshl_add_u64 v[230:231], v[134:135], 0, v[186:187]
	v_lshlrev_b64 v[134:135], 1, v[230:231]
	v_lshl_add_u64 v[136:137], s[20:21], 0, v[134:135]
	v_add_u32_e32 v251, s55, v253
	ds_read_b128 v[206:209], v251
	v_lshl_add_u64 v[136:137], s[8:9], 0, v[134:135]
	v_add_u32_e32 v251, s55, v253
	ds_read_b128 v[210:213], v251 offset:8192
	v_or_b32_e32 v134, 0x100, v134
	v_lshl_add_u64 v[138:139], s[8:9], 0, v[134:135]
	v_lshl_add_u64 v[134:135], s[20:21], 0, v[134:135]
	v_add_u32_e32 v251, s56, v253
	ds_read_b128 v[214:217], v251
	v_add_u32_e32 v251, s56, v253
	ds_read_b128 v[218:221], v251 offset:8192
	v_lshlrev_b64 v[132:133], 10, v[132:133]
	s_waitcnt lgkmcnt(0)
	v_mul_f32_e32 v194, 0xbfb8aa3b, v194
	v_pk_mul_f32 v[120:121], v[120:121], v[194:195] op_sel_hi:[1,0]
	v_lshl_add_u64 v[196:197], v[132:133], 0, v[186:187]
	v_pk_mul_f32 v[126:127], v[126:127], v[194:195] op_sel_hi:[1,0]
	v_exp_f32_e32 v236, v120
	v_exp_f32_e32 v237, v121
	v_lshlrev_b64 v[120:121], 1, v[196:197]
	v_lshlrev_b64 v[128:129], 10, v[128:129]
	v_exp_f32_e32 v234, v126
	v_exp_f32_e32 v235, v127
	v_lshl_add_u64 v[126:127], s[8:9], 0, v[120:121]
	v_lshl_add_u64 v[190:191], v[128:129], 0, v[186:187]
	v_lshl_add_u64 v[128:129], s[20:21], 0, v[120:121]
	v_add_u32_e32 v251, s44, v252
	ds_read_b128 v[222:225], v251
	v_add_u32_e32 v251, s45, v252
	ds_read_b128 v[226:229], v251
	v_lshlrev_b64 v[130:131], 10, v[130:131]
	v_pk_mul_f32 v[124:125], v[124:125], v[194:195] op_sel_hi:[1,0]
	v_pk_mul_f32 v[122:123], v[122:123], v[194:195] op_sel_hi:[1,0]
	v_lshl_add_u64 v[192:193], v[130:131], 0, v[186:187]
	v_exp_f32_e32 v232, v124
	v_exp_f32_e32 v233, v125
	v_exp_f32_e32 v238, v122
	v_exp_f32_e32 v239, v123
	v_lshlrev_b64 v[122:123], 1, v[192:193]
	v_lshlrev_b64 v[124:125], 1, v[190:191]
	v_or_b32_e32 v120, 0x100, v120
	v_lshl_add_u64 v[130:131], s[8:9], 0, v[122:123]
	v_lshl_add_u64 v[132:133], s[20:21], 0, v[122:123]
	v_or_b32_e32 v122, 0x100, v122
	v_lshl_add_u64 v[136:137], s[8:9], 0, v[124:125]
	v_lshl_add_u64 v[134:135], s[20:21], 0, v[124:125]
	v_or_b32_e32 v124, 0x100, v124
	v_lshl_add_u64 v[126:127], s[8:9], 0, v[120:121]
	v_lshl_add_u64 v[120:121], s[20:21], 0, v[120:121]
	v_lshl_add_u64 v[138:139], s[8:9], 0, v[122:123]
	v_lshl_add_u64 v[122:123], s[20:21], 0, v[122:123]
	v_lshl_add_u64 v[240:241], s[8:9], 0, v[124:125]
	v_lshl_add_u64 v[124:125], s[20:21], 0, v[124:125]
	v_add_u32_e32 v251, s46, v252
	ds_read_b128 v[144:147], v251
	v_add_u32_e32 v251, s47, v252
	ds_read_b128 v[148:151], v251
	s_nop 0
	v_add_u32_e32 v251, 0x18000, v253
	ds_read_b128 v[128:131], v251
	s_nop 0
	v_add_u32_e32 v251, 0x18000, v253
	ds_read_b128 v[132:135], v251 offset:8192
	s_nop 0
	v_add_u32_e32 v251, 0x1c000, v253
	ds_read_b128 v[152:155], v251
	v_add_u32_e32 v251, 0x1c000, v253
	ds_read_b128 v[156:159], v251 offset:8192
	s_nop 0
	v_add_u32_e32 v251, s52, v252
	ds_read_b128 v[136:139], v251
	s_nop 0
	v_add_u32_e32 v251, s53, v252
	ds_read_b128 v[140:143], v251
	s_nop 0
	global_load_dwordx4 v[120:123], v[240:241], off
	s_nop 0
	global_load_dwordx4 v[124:127], v[124:125], off
	v_pk_mul_f32 v[118:119], v[118:119], v[194:195] op_sel_hi:[1,0]
	v_pk_mul_f32 v[116:117], v[116:117], v[194:195] op_sel_hi:[1,0]
	v_pk_add_f32 v[234:235], v[234:235], 1.0 op_sel_hi:[1,0]
	v_pk_add_f32 v[232:233], v[232:233], 1.0 op_sel_hi:[1,0]
	v_pk_mul_f32 v[114:115], v[114:115], v[194:195] op_sel_hi:[1,0]
	v_pk_mul_f32 v[112:113], v[112:113], v[194:195] op_sel_hi:[1,0]
	v_exp_f32_e32 v116, v116
	v_exp_f32_e32 v117, v117
	v_exp_f32_e32 v118, v118
	v_exp_f32_e32 v119, v119
	v_pk_add_f32 v[238:239], v[238:239], 1.0 op_sel_hi:[1,0]
	v_pk_add_f32 v[236:237], v[236:237], 1.0 op_sel_hi:[1,0]
	v_rcp_f32_e32 v232, v232
	v_rcp_f32_e32 v233, v233
	v_rcp_f32_e32 v234, v234
	v_rcp_f32_e32 v235, v235
	v_exp_f32_e32 v112, v112
	v_exp_f32_e32 v114, v114
	v_exp_f32_e32 v115, v115
	v_exp_f32_e32 v113, v113
	v_rcp_f32_e32 v236, v236
	v_rcp_f32_e32 v237, v237
	v_rcp_f32_e32 v238, v238
	v_rcp_f32_e32 v239, v239
	v_pk_add_f32 v[118:119], v[118:119], 1.0 op_sel_hi:[1,0]
	v_pk_add_f32 v[116:117], v[116:117], 1.0 op_sel_hi:[1,0]
	v_lshl_add_u64 v[230:231], v[230:231], 2, s[50:51]
	v_pk_add_f32 v[114:115], v[114:115], 1.0 op_sel_hi:[1,0]
	v_pk_add_f32 v[112:113], v[112:113], 1.0 op_sel_hi:[1,0]
	v_rcp_f32_e32 v116, v116
	v_rcp_f32_e32 v117, v117
	v_rcp_f32_e32 v118, v118
	s_waitcnt lgkmcnt(0)
;     __device__ __forceinline__ void operator()(const f32x4 (&acc)[2][2][4][2], const Unit& u, int wr, int wc, int fr, int fq) const {
;     ...
;             for (int m = 0; m < 4; ++m) { const int row = row0 + ai * HALF + m * 16; const float r = rs[ai][m];
; #pragma unroll
;                 for (int bj = 0; bj < 2; ++bj) { const size_t off = (size_t)row * DM + col0 + bj * HALF;
;                     const u32x4 pr = prv[m][bj], xb = xbv[m][bj];
;                     const float rl = -LOG2E * r;
;                     const f32x4 t0 = acc[ai][bj][m][0] * rl, t1 = acc[ai][bj][m][1] * rl;
;                     const f32x4 d0 = (f32x4){__builtin_amdgcn_exp2f(t0[0]), __builtin_amdgcn_exp2f(t0[1]), __builtin_amdgcn_exp2f(t0[2]), __builtin_amdgcn_exp2f(t0[3])} + 1.f;
;                     const f32x4 d1 = (f32x4){__builtin_amdgcn_exp2f(t1[0]), __builtin_amdgcn_exp2f(t1[1]), __builtin_amdgcn_exp2f(t1[2]), __builtin_amdgcn_exp2f(t1[3])} + 1.f;
;                     const f32x4 s0 = (f32x4){__builtin_amdgcn_rcpf(d0[0]), __builtin_amdgcn_rcpf(d0[1]), __builtin_amdgcn_rcpf(d0[2]), __builtin_amdgcn_rcpf(d0[3])}, s1 = (f32x4){__builtin_amdgcn_rcpf(d1[0]), __builtin_amdgcn_rcpf(d1[1]), __builtin_amdgcn_rcpf(d1[2]), __builtin_amdgcn_rcpf(d1[3])};
;                     const f32x4 x0 = (f32x4){__builtin_bit_cast(float, xb.x << 16), __builtin_bit_cast(float, xb.x & 0xffff0000u), __builtin_bit_cast(float, xb.y << 16), __builtin_bit_cast(float, xb.y & 0xffff0000u)};
;                     const f32x4 x1 = (f32x4){__builtin_bit_cast(float, xb.z << 16), __builtin_bit_cast(float, xb.z & 0xffff0000u), __builtin_bit_cast(float, xb.w << 16), __builtin_bit_cast(float, xb.w & 0xffff0000u)};
;                     const f32x4 p0 = (f32x4){__builtin_bit_cast(float, pr.x << 16), __builtin_bit_cast(float, pr.x & 0xffff0000u), __builtin_bit_cast(float, pr.y << 16), __builtin_bit_cast(float, pr.y & 0xffff0000u)};
;                     const f32x4 p1 = (f32x4){__builtin_bit_cast(float, pr.z << 16), __builtin_bit_cast(float, pr.z & 0xffff0000u), __builtin_bit_cast(float, pr.w << 16), __builtin_bit_cast(float, pr.w & 0xffff0000u)};
;                     const f32x4 o0 = s0 * p0 + x0, o1 = s1 * p1 + x1;
;                     __builtin_nontemporal_store(o0, (f32x4*)(out + off)); __builtin_nontemporal_store(o1, (f32x4*)(out + off + 4)); } }
.Lp6x_join:
	v_lshlrev_b32_e32 v240, 16, v206
	v_and_b32_e32 v241, 0xffff0000, v206
	v_lshlrev_b32_e32 v206, 16, v207
	v_and_b32_e32 v207, 0xffff0000, v207
	v_lshlrev_b32_e32 v242, 16, v208
	v_and_b32_e32 v243, 0xffff0000, v208
	v_lshlrev_b32_e32 v244, 16, v209
	v_and_b32_e32 v245, 0xffff0000, v209
	v_lshlrev_b32_e32 v246, 16, v210
	v_and_b32_e32 v247, 0xffff0000, v210
	v_lshlrev_b32_e32 v208, 16, v211
	v_and_b32_e32 v209, 0xffff0000, v211
	v_lshlrev_b32_e32 v210, 16, v212
	v_and_b32_e32 v211, 0xffff0000, v212
	v_lshlrev_b32_e32 v212, 16, v213
	v_and_b32_e32 v213, 0xffff0000, v213
	v_pk_fma_f32 v[208:209], v[234:235], v[208:209], v[206:207]
	v_pk_fma_f32 v[206:207], v[232:233], v[246:247], v[240:241]
	v_rcp_f32_e32 v119, v119
	v_pk_fma_f32 v[212:213], v[238:239], v[212:213], v[244:245]
	v_pk_fma_f32 v[210:211], v[236:237], v[210:211], v[242:243]
	global_store_dwordx4 v[230:231], v[206:209], off nt
	global_store_dwordx4 v[230:231], v[210:213], off offset:16 nt
	v_lshlrev_b32_e32 v194, 16, v229
	v_rcp_f32_e32 v206, v112
	v_rcp_f32_e32 v207, v113
	v_rcp_f32_e32 v208, v114
	v_rcp_f32_e32 v209, v115
	v_lshlrev_b32_e32 v112, 16, v218
	v_and_b32_e32 v113, 0xffff0000, v218
	v_lshlrev_b32_e32 v114, 16, v219
	v_and_b32_e32 v115, 0xffff0000, v219
	v_lshlrev_b32_e32 v218, 16, v214
	v_and_b32_e32 v219, 0xffff0000, v214
	v_lshlrev_b32_e32 v214, 16, v215
	v_and_b32_e32 v215, 0xffff0000, v215
	v_lshlrev_b32_e32 v210, 16, v220
	v_and_b32_e32 v211, 0xffff0000, v220
	v_lshlrev_b32_e32 v212, 16, v221
	v_and_b32_e32 v213, 0xffff0000, v221
	v_lshlrev_b32_e32 v220, 16, v216
	v_and_b32_e32 v221, 0xffff0000, v216
	v_lshlrev_b32_e32 v216, 16, v217
	v_and_b32_e32 v217, 0xffff0000, v217
	v_pk_fma_f32 v[114:115], v[118:119], v[214:215], v[114:115]
	v_pk_fma_f32 v[112:113], v[116:117], v[218:219], v[112:113]
	v_pk_fma_f32 v[118:119], v[208:209], v[216:217], v[212:213]
	v_pk_fma_f32 v[116:117], v[206:207], v[220:221], v[210:211]
	global_store_dwordx4 v[230:231], v[112:115], off offset:512 nt
	global_store_dwordx4 v[230:231], v[116:119], off offset:528 nt
	v_lshlrev_b32_e32 v206, 16, v222
	v_mul_f32_e32 v112, 0xbfb8aa3b, v195
	v_pk_mul_f32 v[110:111], v[110:111], v[112:113] op_sel_hi:[1,0]
	v_pk_mul_f32 v[108:109], v[108:109], v[112:113] op_sel_hi:[1,0]
	v_pk_mul_f32 v[104:105], v[104:105], v[112:113] op_sel_hi:[1,0]
	v_pk_mul_f32 v[106:107], v[106:107], v[112:113] op_sel_hi:[1,0]
	v_exp_f32_e32 v108, v108
	v_exp_f32_e32 v109, v109
	v_exp_f32_e32 v110, v110
	v_exp_f32_e32 v111, v111
	v_exp_f32_e32 v104, v104
	v_exp_f32_e32 v105, v105
	v_exp_f32_e32 v106, v106
	v_exp_f32_e32 v107, v107
	v_pk_mul_f32 v[102:103], v[102:103], v[112:113] op_sel_hi:[1,0]
	v_pk_mul_f32 v[100:101], v[100:101], v[112:113] op_sel_hi:[1,0]
	v_pk_add_f32 v[110:111], v[110:111], 1.0 op_sel_hi:[1,0]
	v_pk_add_f32 v[108:109], v[108:109], 1.0 op_sel_hi:[1,0]
	v_pk_add_f32 v[104:105], v[104:105], 1.0 op_sel_hi:[1,0]
	v_pk_mul_f32 v[98:99], v[98:99], v[112:113] op_sel_hi:[1,0]
	v_pk_mul_f32 v[96:97], v[96:97], v[112:113] op_sel_hi:[1,0]
	v_exp_f32_e32 v100, v100
	v_exp_f32_e32 v101, v101
	v_exp_f32_e32 v102, v102
	v_exp_f32_e32 v103, v103
	v_pk_add_f32 v[106:107], v[106:107], 1.0 op_sel_hi:[1,0]
	v_rcp_f32_e32 v108, v108
	v_rcp_f32_e32 v109, v109
	v_rcp_f32_e32 v110, v110
	v_rcp_f32_e32 v111, v111
	v_rcp_f32_e32 v114, v104
	v_rcp_f32_e32 v115, v105
	v_exp_f32_e32 v96, v96
	v_exp_f32_e32 v98, v98
	v_exp_f32_e32 v99, v99
	v_exp_f32_e32 v97, v97
	v_rcp_f32_e32 v116, v106
	v_rcp_f32_e32 v117, v107
	v_lshlrev_b32_e32 v104, 16, v226
	v_and_b32_e32 v105, 0xffff0000, v226
	v_lshlrev_b32_e32 v106, 16, v227
	v_and_b32_e32 v107, 0xffff0000, v227
	v_lshlrev_b32_e32 v118, 16, v228
	v_and_b32_e32 v119, 0xffff0000, v228
	v_and_b32_e32 v207, 0xffff0000, v222
	v_lshlrev_b32_e32 v208, 16, v223
	v_and_b32_e32 v209, 0xffff0000, v223
	v_lshlrev_b32_e32 v210, 16, v224
	v_and_b32_e32 v211, 0xffff0000, v224
	v_pk_add_f32 v[102:103], v[102:103], 1.0 op_sel_hi:[1,0]
	v_pk_add_f32 v[100:101], v[100:101], 1.0 op_sel_hi:[1,0]
	v_and_b32_e32 v195, 0xffff0000, v229
	v_lshlrev_b32_e32 v212, 16, v225
	v_and_b32_e32 v213, 0xffff0000, v225
	v_pk_fma_f32 v[106:107], v[110:111], v[208:209], v[106:107]
	v_pk_fma_f32 v[104:105], v[108:109], v[206:207], v[104:105]
	v_pk_fma_f32 v[108:109], v[114:115], v[210:211], v[118:119]
	v_lshl_add_u64 v[114:115], v[196:197], 2, s[50:51]
	v_pk_add_f32 v[98:99], v[98:99], 1.0 op_sel_hi:[1,0]
	v_pk_add_f32 v[96:97], v[96:97], 1.0 op_sel_hi:[1,0]
	v_rcp_f32_e32 v100, v100
	v_rcp_f32_e32 v101, v101
	v_rcp_f32_e32 v102, v102
	v_rcp_f32_e32 v103, v103
	v_pk_fma_f32 v[110:111], v[116:117], v[212:213], v[194:195]
	global_store_dwordx4 v[114:115], v[104:107], off nt
	global_store_dwordx4 v[114:115], v[108:111], off offset:16 nt
	v_lshlrev_b32_e32 v112, 16, v152
	v_rcp_f32_e32 v104, v96
	v_rcp_f32_e32 v105, v97
	v_rcp_f32_e32 v106, v98
	v_rcp_f32_e32 v107, v99
	v_lshlrev_b32_e32 v96, 16, v156
	v_and_b32_e32 v97, 0xffff0000, v156
	v_lshlrev_b32_e32 v98, 16, v157
	v_and_b32_e32 v99, 0xffff0000, v157
	v_and_b32_e32 v113, 0xffff0000, v152
	v_lshlrev_b32_e32 v116, 16, v153
	v_and_b32_e32 v117, 0xffff0000, v153
	v_lshlrev_b32_e32 v108, 16, v158
	v_and_b32_e32 v109, 0xffff0000, v158
	v_lshlrev_b32_e32 v110, 16, v159
	v_and_b32_e32 v111, 0xffff0000, v159
	v_lshlrev_b32_e32 v118, 16, v154
	v_and_b32_e32 v119, 0xffff0000, v154
	v_lshlrev_b32_e32 v152, 16, v155
	v_and_b32_e32 v153, 0xffff0000, v155
	v_pk_fma_f32 v[98:99], v[102:103], v[116:117], v[98:99]
	v_pk_fma_f32 v[96:97], v[100:101], v[112:113], v[96:97]
	v_pk_fma_f32 v[102:103], v[106:107], v[152:153], v[110:111]
	v_pk_fma_f32 v[100:101], v[104:105], v[118:119], v[108:109]
;     __device__ __forceinline__ void operator()(const f32x4 (&acc)[2][2][4][2], const Unit& u, int wr, int wc, int fr, int fq) const {
;     ...
;             for (int m = 0; m < 4; ++m) { const int row = row0 + ai * HALF + m * 16; const float r = rs[ai][m];
; #pragma unroll
;                 for (int bj = 0; bj < 2; ++bj) { const size_t off = (size_t)row * DM + col0 + bj * HALF;
;                     const u32x4 pr = prv[m][bj], xb = xbv[m][bj];
;                     const float rl = -LOG2E * r;
;                     const f32x4 t0 = acc[ai][bj][m][0] * rl, t1 = acc[ai][bj][m][1] * rl;
;                     const f32x4 d0 = (f32x4){__builtin_amdgcn_exp2f(t0[0]), __builtin_amdgcn_exp2f(t0[1]), __builtin_amdgcn_exp2f(t0[2]), __builtin_amdgcn_exp2f(t0[3])} + 1.f;
;                     const f32x4 d1 = (f32x4){__builtin_amdgcn_exp2f(t1[0]), __builtin_amdgcn_exp2f(t1[1]), __builtin_amdgcn_exp2f(t1[2]), __builtin_amdgcn_exp2f(t1[3])} + 1.f;
;                     const f32x4 s0 = (f32x4){__builtin_amdgcn_rcpf(d0[0]), __builtin_amdgcn_rcpf(d0[1]), __builtin_amdgcn_rcpf(d0[2]), __builtin_amdgcn_rcpf(d0[3])}, s1 = (f32x4){__builtin_amdgcn_rcpf(d1[0]), __builtin_amdgcn_rcpf(d1[1]), __builtin_amdgcn_rcpf(d1[2]), __builtin_amdgcn_rcpf(d1[3])};
;                     const f32x4 x0 = (f32x4){__builtin_bit_cast(float, xb.x << 16), __builtin_bit_cast(float, xb.x & 0xffff0000u), __builtin_bit_cast(float, xb.y << 16), __builtin_bit_cast(float, xb.y & 0xffff0000u)};
;                     const f32x4 x1 = (f32x4){__builtin_bit_cast(float, xb.z << 16), __builtin_bit_cast(float, xb.z & 0xffff0000u), __builtin_bit_cast(float, xb.w << 16), __builtin_bit_cast(float, xb.w & 0xffff0000u)};
;                     const f32x4 p0 = (f32x4){__builtin_bit_cast(float, pr.x << 16), __builtin_bit_cast(float, pr.x & 0xffff0000u), __builtin_bit_cast(float, pr.y << 16), __builtin_bit_cast(float, pr.y & 0xffff0000u)};
;                     const f32x4 p1 = (f32x4){__builtin_bit_cast(float, pr.z << 16), __builtin_bit_cast(float, pr.z & 0xffff0000u), __builtin_bit_cast(float, pr.w << 16), __builtin_bit_cast(float, pr.w & 0xffff0000u)};
;                     const f32x4 o0 = s0 * p0 + x0, o1 = s1 * p1 + x1;
;                     __builtin_nontemporal_store(o0, (f32x4*)(out + off)); __builtin_nontemporal_store(o1, (f32x4*)(out + off + 4)); } }
	global_store_dwordx4 v[114:115], v[96:99], off offset:512 nt
	global_store_dwordx4 v[114:115], v[100:103], off offset:528 nt
	v_lshlrev_b32_e32 v106, 16, v144
	v_mul_f32_e32 v96, 0xbfb8aa3b, v188
	v_pk_mul_f32 v[94:95], v[94:95], v[96:97] op_sel_hi:[1,0]
	v_pk_mul_f32 v[92:93], v[92:93], v[96:97] op_sel_hi:[1,0]
	v_pk_mul_f32 v[88:89], v[88:89], v[96:97] op_sel_hi:[1,0]
	v_pk_mul_f32 v[90:91], v[90:91], v[96:97] op_sel_hi:[1,0]
	v_exp_f32_e32 v92, v92
	v_exp_f32_e32 v93, v93
	v_exp_f32_e32 v94, v94
	v_exp_f32_e32 v95, v95
	v_exp_f32_e32 v88, v88
	v_exp_f32_e32 v89, v89
	v_exp_f32_e32 v90, v90
	v_exp_f32_e32 v91, v91
	v_pk_mul_f32 v[86:87], v[86:87], v[96:97] op_sel_hi:[1,0]
	v_pk_mul_f32 v[84:85], v[84:85], v[96:97] op_sel_hi:[1,0]
	v_pk_add_f32 v[94:95], v[94:95], 1.0 op_sel_hi:[1,0]
	v_pk_add_f32 v[92:93], v[92:93], 1.0 op_sel_hi:[1,0]
	v_pk_add_f32 v[88:89], v[88:89], 1.0 op_sel_hi:[1,0]
	v_pk_mul_f32 v[82:83], v[82:83], v[96:97] op_sel_hi:[1,0]
	v_pk_mul_f32 v[80:81], v[80:81], v[96:97] op_sel_hi:[1,0]
	v_exp_f32_e32 v84, v84
	v_exp_f32_e32 v85, v85
	v_exp_f32_e32 v86, v86
	v_exp_f32_e32 v87, v87
	v_pk_add_f32 v[90:91], v[90:91], 1.0 op_sel_hi:[1,0]
	v_rcp_f32_e32 v92, v92
	v_rcp_f32_e32 v93, v93
	v_rcp_f32_e32 v94, v94
	v_rcp_f32_e32 v95, v95
	v_rcp_f32_e32 v98, v88
	v_rcp_f32_e32 v99, v89
	v_exp_f32_e32 v80, v80
	v_exp_f32_e32 v82, v82
	v_exp_f32_e32 v83, v83
	v_exp_f32_e32 v81, v81
	v_rcp_f32_e32 v100, v90
	v_rcp_f32_e32 v101, v91
	v_lshlrev_b32_e32 v88, 16, v148
	v_and_b32_e32 v89, 0xffff0000, v148
	v_lshlrev_b32_e32 v90, 16, v149
	v_and_b32_e32 v91, 0xffff0000, v149
	v_lshlrev_b32_e32 v102, 16, v150
	v_and_b32_e32 v103, 0xffff0000, v150
	v_and_b32_e32 v107, 0xffff0000, v144
	v_lshlrev_b32_e32 v108, 16, v145
	v_and_b32_e32 v109, 0xffff0000, v145
	v_lshlrev_b32_e32 v110, 16, v146
	v_and_b32_e32 v111, 0xffff0000, v146
	v_pk_add_f32 v[86:87], v[86:87], 1.0 op_sel_hi:[1,0]
	v_pk_add_f32 v[84:85], v[84:85], 1.0 op_sel_hi:[1,0]
	v_lshlrev_b32_e32 v104, 16, v151
	v_and_b32_e32 v105, 0xffff0000, v151
	v_lshlrev_b32_e32 v112, 16, v147
	v_and_b32_e32 v113, 0xffff0000, v147
	v_pk_fma_f32 v[90:91], v[94:95], v[108:109], v[90:91]
	v_pk_fma_f32 v[88:89], v[92:93], v[106:107], v[88:89]
	v_pk_fma_f32 v[92:93], v[98:99], v[110:111], v[102:103]
	v_lshl_add_u64 v[98:99], v[192:193], 2, s[50:51]
	v_pk_add_f32 v[82:83], v[82:83], 1.0 op_sel_hi:[1,0]
	v_pk_add_f32 v[80:81], v[80:81], 1.0 op_sel_hi:[1,0]
	v_rcp_f32_e32 v84, v84
	v_rcp_f32_e32 v85, v85
	v_rcp_f32_e32 v86, v86
	v_rcp_f32_e32 v87, v87
	v_pk_fma_f32 v[94:95], v[100:101], v[112:113], v[104:105]
	global_store_dwordx4 v[98:99], v[88:91], off nt
	global_store_dwordx4 v[98:99], v[92:95], off offset:16 nt
	v_lshlrev_b32_e32 v96, 16, v136
	v_rcp_f32_e32 v88, v80
	v_rcp_f32_e32 v89, v81
	v_rcp_f32_e32 v90, v82
	v_rcp_f32_e32 v91, v83
	v_lshlrev_b32_e32 v80, 16, v140
	v_and_b32_e32 v81, 0xffff0000, v140
	v_lshlrev_b32_e32 v82, 16, v141
	v_and_b32_e32 v83, 0xffff0000, v141
	v_and_b32_e32 v97, 0xffff0000, v136
	v_lshlrev_b32_e32 v100, 16, v137
	v_and_b32_e32 v101, 0xffff0000, v137
	v_lshlrev_b32_e32 v92, 16, v142
	v_and_b32_e32 v93, 0xffff0000, v142
	v_lshlrev_b32_e32 v94, 16, v143
	v_and_b32_e32 v95, 0xffff0000, v143
	v_lshlrev_b32_e32 v102, 16, v138
	v_and_b32_e32 v103, 0xffff0000, v138
	v_lshlrev_b32_e32 v104, 16, v139
	v_and_b32_e32 v105, 0xffff0000, v139
	v_pk_fma_f32 v[82:83], v[86:87], v[100:101], v[82:83]
	v_pk_fma_f32 v[80:81], v[84:85], v[96:97], v[80:81]
	v_pk_fma_f32 v[86:87], v[90:91], v[104:105], v[94:95]
	v_pk_fma_f32 v[84:85], v[88:89], v[102:103], v[92:93]
	global_store_dwordx4 v[98:99], v[80:83], off offset:512 nt
	global_store_dwordx4 v[98:99], v[84:87], off offset:528 nt
	v_lshlrev_b32_e32 v90, 16, v128
	v_mul_f32_e32 v80, 0xbfb8aa3b, v189
	v_pk_mul_f32 v[78:79], v[78:79], v[80:81] op_sel_hi:[1,0]
	v_pk_mul_f32 v[76:77], v[76:77], v[80:81] op_sel_hi:[1,0]
	v_pk_mul_f32 v[72:73], v[72:73], v[80:81] op_sel_hi:[1,0]
	v_pk_mul_f32 v[74:75], v[74:75], v[80:81] op_sel_hi:[1,0]
	v_exp_f32_e32 v76, v76
	v_exp_f32_e32 v77, v77
	v_exp_f32_e32 v78, v78
	v_exp_f32_e32 v79, v79
	v_exp_f32_e32 v72, v72
	v_exp_f32_e32 v73, v73
	v_exp_f32_e32 v74, v74
	v_exp_f32_e32 v75, v75
	v_pk_mul_f32 v[70:71], v[70:71], v[80:81] op_sel_hi:[1,0]
	v_pk_mul_f32 v[68:69], v[68:69], v[80:81] op_sel_hi:[1,0]
	v_pk_add_f32 v[78:79], v[78:79], 1.0 op_sel_hi:[1,0]
	v_pk_add_f32 v[76:77], v[76:77], 1.0 op_sel_hi:[1,0]
	v_pk_add_f32 v[72:73], v[72:73], 1.0 op_sel_hi:[1,0]
	v_pk_mul_f32 v[66:67], v[66:67], v[80:81] op_sel_hi:[1,0]
	v_pk_mul_f32 v[64:65], v[64:65], v[80:81] op_sel_hi:[1,0]
	v_exp_f32_e32 v68, v68
	v_exp_f32_e32 v69, v69
	v_exp_f32_e32 v70, v70
	v_exp_f32_e32 v71, v71
	v_pk_add_f32 v[74:75], v[74:75], 1.0 op_sel_hi:[1,0]
	v_rcp_f32_e32 v76, v76
	v_rcp_f32_e32 v77, v77
	v_rcp_f32_e32 v78, v78
	v_rcp_f32_e32 v79, v79
	v_rcp_f32_e32 v82, v72
	v_rcp_f32_e32 v83, v73
	v_exp_f32_e32 v64, v64
	v_exp_f32_e32 v66, v66
	v_exp_f32_e32 v67, v67
	v_exp_f32_e32 v65, v65
	v_rcp_f32_e32 v84, v74
	v_rcp_f32_e32 v85, v75
	v_lshlrev_b32_e32 v72, 16, v132
	v_and_b32_e32 v73, 0xffff0000, v132
	v_lshlrev_b32_e32 v74, 16, v133
	v_and_b32_e32 v75, 0xffff0000, v133
	v_lshlrev_b32_e32 v86, 16, v134
	v_and_b32_e32 v87, 0xffff0000, v134
	v_and_b32_e32 v91, 0xffff0000, v128
	v_lshlrev_b32_e32 v92, 16, v129
	v_and_b32_e32 v93, 0xffff0000, v129
	v_lshlrev_b32_e32 v94, 16, v130
	v_and_b32_e32 v95, 0xffff0000, v130
	v_pk_add_f32 v[70:71], v[70:71], 1.0 op_sel_hi:[1,0]
	v_pk_add_f32 v[68:69], v[68:69], 1.0 op_sel_hi:[1,0]
	v_lshlrev_b32_e32 v88, 16, v135
	v_and_b32_e32 v89, 0xffff0000, v135
	v_lshlrev_b32_e32 v96, 16, v131
	v_and_b32_e32 v97, 0xffff0000, v131
	v_pk_fma_f32 v[74:75], v[78:79], v[92:93], v[74:75]
	v_pk_fma_f32 v[72:73], v[76:77], v[90:91], v[72:73]
	v_pk_fma_f32 v[76:77], v[82:83], v[94:95], v[86:87]
	v_lshl_add_u64 v[82:83], v[190:191], 2, s[50:51]
	v_pk_add_f32 v[66:67], v[66:67], 1.0 op_sel_hi:[1,0]
	v_pk_add_f32 v[64:65], v[64:65], 1.0 op_sel_hi:[1,0]
	v_rcp_f32_e32 v68, v68
	v_rcp_f32_e32 v69, v69
	v_rcp_f32_e32 v70, v70
	v_rcp_f32_e32 v71, v71
	v_pk_fma_f32 v[78:79], v[84:85], v[96:97], v[88:89]
	global_store_dwordx4 v[82:83], v[72:75], off nt
	global_store_dwordx4 v[82:83], v[76:79], off offset:16 nt
	s_waitcnt vmcnt(14)
;     __device__ __forceinline__ void operator()(const f32x4 (&acc)[2][2][4][2], const Unit& u, int wr, int wc, int fr, int fq) const {
;     ...
;         for (int ai = 0; ai < 2; ++ai) {
;             u32x4 prv[4][2], xbv[4][2];
; #pragma unroll
;             for (int m = 0; m < 4; ++m)
; #pragma unroll
;                 for (int bj = 0; bj < 2; ++bj) { const size_t off = (size_t)(row0 + ai * HALF + m * 16) * DM + col0 + bj * HALF; prv[m][bj] = *(const u32x4*)(PR + off); xbv[m][bj] = *(const u32x4*)(Xb + off); }
; #pragma unroll
;             for (int m = 0; m < 4; ++m) { const int row = row0 + ai * HALF + m * 16; const float r = rs[ai][m];
; #pragma unroll
;                 for (int bj = 0; bj < 2; ++bj) { const size_t off = (size_t)row * DM + col0 + bj * HALF;
;                     const u32x4 pr = prv[m][bj], xb = xbv[m][bj];
;                     const float rl = -LOG2E * r;
;                     const f32x4 t0 = acc[ai][bj][m][0] * rl, t1 = acc[ai][bj][m][1] * rl;
;                     const f32x4 d0 = (f32x4){__builtin_amdgcn_exp2f(t0[0]), __builtin_amdgcn_exp2f(t0[1]), __builtin_amdgcn_exp2f(t0[2]), __builtin_amdgcn_exp2f(t0[3])} + 1.f;
;                     const f32x4 d1 = (f32x4){__builtin_amdgcn_exp2f(t1[0]), __builtin_amdgcn_exp2f(t1[1]), __builtin_amdgcn_exp2f(t1[2]), __builtin_amdgcn_exp2f(t1[3])} + 1.f;
;                     const f32x4 s0 = (f32x4){__builtin_amdgcn_rcpf(d0[0]), __builtin_amdgcn_rcpf(d0[1]), __builtin_amdgcn_rcpf(d0[2]), __builtin_amdgcn_rcpf(d0[3])}, s1 = (f32x4){__builtin_amdgcn_rcpf(d1[0]), __builtin_amdgcn_rcpf(d1[1]), __builtin_amdgcn_rcpf(d1[2]), __builtin_amdgcn_rcpf(d1[3])};
;                     const f32x4 x0 = (f32x4){__builtin_bit_cast(float, xb.x << 16), __builtin_bit_cast(float, xb.x & 0xffff0000u), __builtin_bit_cast(float, xb.y << 16), __builtin_bit_cast(float, xb.y & 0xffff0000u)};
;                     const f32x4 x1 = (f32x4){__builtin_bit_cast(float, xb.z << 16), __builtin_bit_cast(float, xb.z & 0xffff0000u), __builtin_bit_cast(float, xb.w << 16), __builtin_bit_cast(float, xb.w & 0xffff0000u)};
;                     const f32x4 p0 = (f32x4){__builtin_bit_cast(float, pr.x << 16), __builtin_bit_cast(float, pr.x & 0xffff0000u), __builtin_bit_cast(float, pr.y << 16), __builtin_bit_cast(float, pr.y & 0xffff0000u)};
	v_lshlrev_b32_e32 v80, 16, v120
	v_rcp_f32_e32 v72, v64
	v_rcp_f32_e32 v73, v65
	v_rcp_f32_e32 v74, v66
	v_rcp_f32_e32 v75, v67
	v_lshlrev_b32_e32 v64, 16, v124
	v_and_b32_e32 v65, 0xffff0000, v124
	v_lshlrev_b32_e32 v66, 16, v125
	v_and_b32_e32 v67, 0xffff0000, v125
	v_and_b32_e32 v81, 0xffff0000, v120
	v_lshlrev_b32_e32 v84, 16, v121
	v_and_b32_e32 v85, 0xffff0000, v121
	v_lshlrev_b32_e32 v76, 16, v126
	v_and_b32_e32 v77, 0xffff0000, v126
	v_lshlrev_b32_e32 v78, 16, v127
	v_and_b32_e32 v79, 0xffff0000, v127
	v_lshlrev_b32_e32 v86, 16, v122
	v_and_b32_e32 v87, 0xffff0000, v122
	v_lshlrev_b32_e32 v88, 16, v123
	v_and_b32_e32 v89, 0xffff0000, v123
	v_pk_fma_f32 v[66:67], v[70:71], v[84:85], v[66:67]
	v_pk_fma_f32 v[64:65], v[68:69], v[80:81], v[64:65]
	v_pk_fma_f32 v[70:71], v[74:75], v[88:89], v[78:79]
	v_pk_fma_f32 v[68:69], v[72:73], v[86:87], v[76:77]
	global_store_dwordx4 v[82:83], v[64:67], off offset:512 nt
	global_store_dwordx4 v[82:83], v[68:71], off offset:528 nt
	v_ashrrev_i32_e32 v183, 31, v182
	v_lshlrev_b64 v[64:65], 10, v[184:185]
	v_lshl_add_u64 v[134:135], v[64:65], 0, v[186:187]
	v_lshlrev_b64 v[64:65], 1, v[134:135]
	v_lshl_add_u64 v[66:67], s[20:21], 0, v[64:65]
	global_load_dwordx4 v[118:121], v[66:67], off
	v_lshl_add_u64 v[66:67], s[8:9], 0, v[64:65]
	global_load_dwordx4 v[122:125], v[66:67], off
	v_or_b32_e32 v64, 0x100, v64
	v_lshl_add_u64 v[66:67], s[8:9], 0, v[64:65]
	v_lshl_add_u64 v[64:65], s[20:21], 0, v[64:65]
	global_load_dwordx4 v[126:129], v[66:67], off
	global_load_dwordx4 v[130:133], v[64:65], off
	v_lshlrev_b64 v[64:65], 10, v[182:183]
	v_lshl_add_u64 v[64:65], v[64:65], 0, v[186:187]
	v_lshl_add_u64 v[116:117], v[64:65], 0, s[24:25]
	v_lshlrev_b64 v[66:67], 1, v[116:117]
	v_lshl_add_u64 v[68:69], s[8:9], 0, v[66:67]
	v_lshl_add_u64 v[70:71], s[20:21], 0, v[66:67]
	global_load_dwordx4 v[104:107], v[68:69], off
	global_load_dwordx4 v[108:111], v[70:71], off
	v_or_b32_e32 v66, 0x100, v66
	v_lshl_add_u64 v[68:69], s[8:9], 0, v[66:67]
	v_lshl_add_u64 v[66:67], s[20:21], 0, v[66:67]
	global_load_dwordx4 v[96:99], v[68:69], off
	global_load_dwordx4 v[100:103], v[66:67], off
	v_lshl_add_u64 v[114:115], v[64:65], 0, s[26:27]
	v_lshlrev_b64 v[66:67], 1, v[114:115]
	v_lshl_add_u64 v[68:69], s[8:9], 0, v[66:67]
	v_lshl_add_u64 v[70:71], s[20:21], 0, v[66:67]
	global_load_dwordx4 v[88:91], v[68:69], off
	global_load_dwordx4 v[92:95], v[70:71], off
	v_or_b32_e32 v66, 0x100, v66
	v_lshl_add_u64 v[68:69], s[8:9], 0, v[66:67]
	v_lshl_add_u64 v[66:67], s[20:21], 0, v[66:67]
	global_load_dwordx4 v[80:83], v[68:69], off
	global_load_dwordx4 v[84:87], v[66:67], off
	v_lshl_add_u64 v[112:113], v[64:65], 0, s[28:29]
	v_lshlrev_b64 v[64:65], 1, v[112:113]
	v_lshl_add_u64 v[66:67], s[8:9], 0, v[64:65]
	v_lshl_add_u64 v[68:69], s[20:21], 0, v[64:65]
	global_load_dwordx4 v[72:75], v[66:67], off
	global_load_dwordx4 v[76:79], v[68:69], off
	v_or_b32_e32 v64, 0x100, v64
	v_lshl_add_u64 v[66:67], s[8:9], 0, v[64:65]
	v_lshl_add_u64 v[68:69], s[20:21], 0, v[64:65]
	global_load_dwordx4 v[64:67], v[66:67], off
	s_nop 0
	global_load_dwordx4 v[68:71], v[68:69], off
	v_mul_f32_e32 v136, 0xbfb8aa3b, v180
	v_pk_mul_f32 v[62:63], v[62:63], v[136:137] op_sel_hi:[1,0]
	v_pk_mul_f32 v[60:61], v[60:61], v[136:137] op_sel_hi:[1,0]
	v_pk_mul_f32 v[56:57], v[56:57], v[136:137] op_sel_hi:[1,0]
	v_pk_mul_f32 v[58:59], v[58:59], v[136:137] op_sel_hi:[1,0]
	v_exp_f32_e32 v60, v60
	v_exp_f32_e32 v61, v61
	v_exp_f32_e32 v62, v62
	v_exp_f32_e32 v63, v63
	v_exp_f32_e32 v56, v56
	v_exp_f32_e32 v57, v57
	v_exp_f32_e32 v58, v58
	v_exp_f32_e32 v59, v59
	v_pk_mul_f32 v[54:55], v[54:55], v[136:137] op_sel_hi:[1,0]
	v_pk_mul_f32 v[52:53], v[52:53], v[136:137] op_sel_hi:[1,0]
	v_pk_add_f32 v[62:63], v[62:63], 1.0 op_sel_hi:[1,0]
	v_pk_add_f32 v[60:61], v[60:61], 1.0 op_sel_hi:[1,0]
	v_pk_add_f32 v[56:57], v[56:57], 1.0 op_sel_hi:[1,0]
	v_pk_mul_f32 v[50:51], v[50:51], v[136:137] op_sel_hi:[1,0]
	v_pk_mul_f32 v[48:49], v[48:49], v[136:137] op_sel_hi:[1,0]
	v_exp_f32_e32 v52, v52
	v_exp_f32_e32 v53, v53
	v_exp_f32_e32 v54, v54
	v_exp_f32_e32 v55, v55
	v_pk_add_f32 v[58:59], v[58:59], 1.0 op_sel_hi:[1,0]
	v_rcp_f32_e32 v60, v60
	v_rcp_f32_e32 v61, v61
	v_rcp_f32_e32 v62, v62
	v_rcp_f32_e32 v63, v63
	v_rcp_f32_e32 v138, v56
	v_rcp_f32_e32 v139, v57
	v_exp_f32_e32 v48, v48
	v_exp_f32_e32 v50, v50
	v_exp_f32_e32 v51, v51
	v_exp_f32_e32 v49, v49
	v_rcp_f32_e32 v140, v58
	v_rcp_f32_e32 v141, v59
	v_pk_add_f32 v[54:55], v[54:55], 1.0 op_sel_hi:[1,0]
	v_pk_add_f32 v[52:53], v[52:53], 1.0 op_sel_hi:[1,0]
	v_pk_add_f32 v[50:51], v[50:51], 1.0 op_sel_hi:[1,0]
	v_pk_add_f32 v[48:49], v[48:49], 1.0 op_sel_hi:[1,0]
	v_rcp_f32_e32 v52, v52
	v_rcp_f32_e32 v53, v53
	v_rcp_f32_e32 v54, v54
	s_waitcnt vmcnt(15)
	v_lshlrev_b32_e32 v56, 16, v118
	v_and_b32_e32 v57, 0xffff0000, v118
	v_lshlrev_b32_e32 v58, 16, v119
	v_and_b32_e32 v59, 0xffff0000, v119
	v_lshlrev_b32_e32 v118, 16, v120
	v_and_b32_e32 v119, 0xffff0000, v120
	s_waitcnt vmcnt(14)
	v_lshlrev_b32_e32 v142, 16, v122
	v_and_b32_e32 v143, 0xffff0000, v122
	v_lshlrev_b32_e32 v122, 16, v123
	v_and_b32_e32 v123, 0xffff0000, v123
	v_lshlrev_b32_e32 v144, 16, v124
	v_and_b32_e32 v145, 0xffff0000, v124
	v_lshlrev_b32_e32 v120, 16, v121
	v_and_b32_e32 v121, 0xffff0000, v121
	v_lshlrev_b32_e32 v124, 16, v125
	v_and_b32_e32 v125, 0xffff0000, v125
	v_pk_fma_f32 v[58:59], v[62:63], v[122:123], v[58:59]
	v_pk_fma_f32 v[56:57], v[60:61], v[142:143], v[56:57]
	v_pk_fma_f32 v[60:61], v[138:139], v[144:145], v[118:119]
	v_lshl_add_u64 v[118:119], v[134:135], 2, s[50:51]
	v_rcp_f32_e32 v55, v55
	v_pk_fma_f32 v[62:63], v[140:141], v[124:125], v[120:121]
	global_store_dwordx4 v[118:119], v[56:59], off nt
	global_store_dwordx4 v[118:119], v[60:63], off offset:16 nt
	s_waitcnt vmcnt(15)
;     __device__ __forceinline__ void operator()(const f32x4 (&acc)[2][2][4][2], const Unit& u, int wr, int wc, int fr, int fq) const {
;     ...
;             for (int m = 0; m < 4; ++m) { const int row = row0 + ai * HALF + m * 16; const float r = rs[ai][m];
; #pragma unroll
;                 for (int bj = 0; bj < 2; ++bj) { const size_t off = (size_t)row * DM + col0 + bj * HALF;
;                     const u32x4 pr = prv[m][bj], xb = xbv[m][bj];
;                     const float rl = -LOG2E * r;
;                     const f32x4 t0 = acc[ai][bj][m][0] * rl, t1 = acc[ai][bj][m][1] * rl;
;                     const f32x4 d0 = (f32x4){__builtin_amdgcn_exp2f(t0[0]), __builtin_amdgcn_exp2f(t0[1]), __builtin_amdgcn_exp2f(t0[2]), __builtin_amdgcn_exp2f(t0[3])} + 1.f;
;                     const f32x4 d1 = (f32x4){__builtin_amdgcn_exp2f(t1[0]), __builtin_amdgcn_exp2f(t1[1]), __builtin_amdgcn_exp2f(t1[2]), __builtin_amdgcn_exp2f(t1[3])} + 1.f;
;                     const f32x4 s0 = (f32x4){__builtin_amdgcn_rcpf(d0[0]), __builtin_amdgcn_rcpf(d0[1]), __builtin_amdgcn_rcpf(d0[2]), __builtin_amdgcn_rcpf(d0[3])}, s1 = (f32x4){__builtin_amdgcn_rcpf(d1[0]), __builtin_amdgcn_rcpf(d1[1]), __builtin_amdgcn_rcpf(d1[2]), __builtin_amdgcn_rcpf(d1[3])};
;                     const f32x4 x0 = (f32x4){__builtin_bit_cast(float, xb.x << 16), __builtin_bit_cast(float, xb.x & 0xffff0000u), __builtin_bit_cast(float, xb.y << 16), __builtin_bit_cast(float, xb.y & 0xffff0000u)};
;                     const f32x4 x1 = (f32x4){__builtin_bit_cast(float, xb.z << 16), __builtin_bit_cast(float, xb.z & 0xffff0000u), __builtin_bit_cast(float, xb.w << 16), __builtin_bit_cast(float, xb.w & 0xffff0000u)};
;                     const f32x4 p0 = (f32x4){__builtin_bit_cast(float, pr.x << 16), __builtin_bit_cast(float, pr.x & 0xffff0000u), __builtin_bit_cast(float, pr.y << 16), __builtin_bit_cast(float, pr.y & 0xffff0000u)};
;                     const f32x4 p1 = (f32x4){__builtin_bit_cast(float, pr.z << 16), __builtin_bit_cast(float, pr.z & 0xffff0000u), __builtin_bit_cast(float, pr.w << 16), __builtin_bit_cast(float, pr.w & 0xffff0000u)};
;                     const f32x4 o0 = s0 * p0 + x0, o1 = s1 * p1 + x1;
;                     __builtin_nontemporal_store(o0, (f32x4*)(out + off)); __builtin_nontemporal_store(o1, (f32x4*)(out + off + 4)); } }
	v_lshlrev_b32_e32 v120, 16, v126
	v_rcp_f32_e32 v56, v48
	v_rcp_f32_e32 v57, v49
	v_rcp_f32_e32 v58, v50
	v_rcp_f32_e32 v59, v51
	s_waitcnt vmcnt(14)
	v_lshlrev_b32_e32 v48, 16, v130
	v_and_b32_e32 v49, 0xffff0000, v130
	v_lshlrev_b32_e32 v50, 16, v131
	v_and_b32_e32 v51, 0xffff0000, v131
	v_and_b32_e32 v121, 0xffff0000, v126
	v_lshlrev_b32_e32 v122, 16, v127
	v_and_b32_e32 v123, 0xffff0000, v127
	v_lshlrev_b32_e32 v60, 16, v132
	v_and_b32_e32 v61, 0xffff0000, v132
	v_lshlrev_b32_e32 v62, 16, v133
	v_and_b32_e32 v63, 0xffff0000, v133
	v_lshlrev_b32_e32 v124, 16, v128
	v_and_b32_e32 v125, 0xffff0000, v128
	v_lshlrev_b32_e32 v126, 16, v129
	v_and_b32_e32 v127, 0xffff0000, v129
	v_pk_fma_f32 v[50:51], v[54:55], v[122:123], v[50:51]
	v_pk_fma_f32 v[48:49], v[52:53], v[120:121], v[48:49]
	v_pk_fma_f32 v[54:55], v[58:59], v[126:127], v[62:63]
	v_pk_fma_f32 v[52:53], v[56:57], v[124:125], v[60:61]
	global_store_dwordx4 v[118:119], v[48:51], off offset:512 nt
	global_store_dwordx4 v[118:119], v[52:55], off offset:528 nt
	s_waitcnt vmcnt(15)
	v_lshlrev_b32_e32 v58, 16, v104
	v_mul_f32_e32 v48, 0xbfb8aa3b, v181
	v_pk_mul_f32 v[46:47], v[46:47], v[48:49] op_sel_hi:[1,0]
	v_pk_mul_f32 v[44:45], v[44:45], v[48:49] op_sel_hi:[1,0]
	v_pk_mul_f32 v[40:41], v[40:41], v[48:49] op_sel_hi:[1,0]
	v_pk_mul_f32 v[42:43], v[42:43], v[48:49] op_sel_hi:[1,0]
	v_exp_f32_e32 v44, v44
	v_exp_f32_e32 v45, v45
	v_exp_f32_e32 v46, v46
	v_exp_f32_e32 v47, v47
	v_exp_f32_e32 v40, v40
	v_exp_f32_e32 v41, v41
	v_exp_f32_e32 v42, v42
	v_exp_f32_e32 v43, v43
	v_pk_mul_f32 v[38:39], v[38:39], v[48:49] op_sel_hi:[1,0]
	v_pk_mul_f32 v[36:37], v[36:37], v[48:49] op_sel_hi:[1,0]
	v_pk_add_f32 v[46:47], v[46:47], 1.0 op_sel_hi:[1,0]
	v_pk_add_f32 v[44:45], v[44:45], 1.0 op_sel_hi:[1,0]
	v_pk_add_f32 v[40:41], v[40:41], 1.0 op_sel_hi:[1,0]
	v_pk_mul_f32 v[34:35], v[34:35], v[48:49] op_sel_hi:[1,0]
	v_pk_mul_f32 v[32:33], v[32:33], v[48:49] op_sel_hi:[1,0]
	v_exp_f32_e32 v36, v36
	v_exp_f32_e32 v37, v37
	v_exp_f32_e32 v38, v38
	v_exp_f32_e32 v39, v39
	v_pk_add_f32 v[42:43], v[42:43], 1.0 op_sel_hi:[1,0]
	v_rcp_f32_e32 v44, v44
	v_rcp_f32_e32 v45, v45
	v_rcp_f32_e32 v46, v46
	v_rcp_f32_e32 v47, v47
	v_rcp_f32_e32 v50, v40
	v_rcp_f32_e32 v51, v41
	v_exp_f32_e32 v32, v32
	v_exp_f32_e32 v34, v34
	v_exp_f32_e32 v35, v35
	v_exp_f32_e32 v33, v33
	v_rcp_f32_e32 v52, v42
	v_rcp_f32_e32 v53, v43
	s_waitcnt vmcnt(14)
	v_lshlrev_b32_e32 v40, 16, v108
	v_and_b32_e32 v41, 0xffff0000, v108
	v_lshlrev_b32_e32 v42, 16, v109
	v_and_b32_e32 v43, 0xffff0000, v109
	v_lshlrev_b32_e32 v54, 16, v110
	v_and_b32_e32 v55, 0xffff0000, v110
	v_and_b32_e32 v59, 0xffff0000, v104
	v_lshlrev_b32_e32 v60, 16, v105
	v_and_b32_e32 v61, 0xffff0000, v105
	v_lshlrev_b32_e32 v62, 16, v106
	v_and_b32_e32 v63, 0xffff0000, v106
	v_pk_add_f32 v[38:39], v[38:39], 1.0 op_sel_hi:[1,0]
	v_pk_add_f32 v[36:37], v[36:37], 1.0 op_sel_hi:[1,0]
	v_lshlrev_b32_e32 v56, 16, v111
	v_and_b32_e32 v57, 0xffff0000, v111
	v_lshlrev_b32_e32 v104, 16, v107
	v_and_b32_e32 v105, 0xffff0000, v107
	v_pk_fma_f32 v[42:43], v[46:47], v[60:61], v[42:43]
	v_pk_fma_f32 v[40:41], v[44:45], v[58:59], v[40:41]
	v_pk_fma_f32 v[44:45], v[50:51], v[62:63], v[54:55]
	v_lshl_add_u64 v[50:51], v[116:117], 2, s[50:51]
	v_pk_add_f32 v[34:35], v[34:35], 1.0 op_sel_hi:[1,0]
	v_pk_add_f32 v[32:33], v[32:33], 1.0 op_sel_hi:[1,0]
	v_rcp_f32_e32 v36, v36
	v_rcp_f32_e32 v37, v37
	v_rcp_f32_e32 v38, v38
	v_rcp_f32_e32 v39, v39
	v_pk_fma_f32 v[46:47], v[52:53], v[104:105], v[56:57]
	global_store_dwordx4 v[50:51], v[40:43], off nt
	global_store_dwordx4 v[50:51], v[44:47], off offset:16 nt
	s_waitcnt vmcnt(15)
	v_lshlrev_b32_e32 v48, 16, v96
	v_rcp_f32_e32 v40, v32
	v_rcp_f32_e32 v41, v33
	v_rcp_f32_e32 v42, v34
	v_rcp_f32_e32 v43, v35
	s_waitcnt vmcnt(14)
	v_lshlrev_b32_e32 v32, 16, v100
	v_and_b32_e32 v33, 0xffff0000, v100
	v_lshlrev_b32_e32 v34, 16, v101
	v_and_b32_e32 v35, 0xffff0000, v101
	v_and_b32_e32 v49, 0xffff0000, v96
	v_lshlrev_b32_e32 v52, 16, v97
	v_and_b32_e32 v53, 0xffff0000, v97
	v_lshlrev_b32_e32 v44, 16, v102
	v_and_b32_e32 v45, 0xffff0000, v102
	v_lshlrev_b32_e32 v46, 16, v103
	v_and_b32_e32 v47, 0xffff0000, v103
	v_lshlrev_b32_e32 v54, 16, v98
	v_and_b32_e32 v55, 0xffff0000, v98
	v_lshlrev_b32_e32 v56, 16, v99
	v_and_b32_e32 v57, 0xffff0000, v99
	v_pk_fma_f32 v[34:35], v[38:39], v[52:53], v[34:35]
	v_pk_fma_f32 v[32:33], v[36:37], v[48:49], v[32:33]
	v_pk_fma_f32 v[38:39], v[42:43], v[56:57], v[46:47]
	v_pk_fma_f32 v[36:37], v[40:41], v[54:55], v[44:45]
	global_store_dwordx4 v[50:51], v[32:35], off offset:512 nt
	global_store_dwordx4 v[50:51], v[36:39], off offset:528 nt
	s_waitcnt vmcnt(15)
	v_lshlrev_b32_e32 v42, 16, v88
	v_mul_f32_e32 v32, 0xbfb8aa3b, v178
	v_pk_mul_f32 v[30:31], v[30:31], v[32:33] op_sel_hi:[1,0]
	v_pk_mul_f32 v[28:29], v[28:29], v[32:33] op_sel_hi:[1,0]
	v_pk_mul_f32 v[24:25], v[24:25], v[32:33] op_sel_hi:[1,0]
	v_pk_mul_f32 v[26:27], v[26:27], v[32:33] op_sel_hi:[1,0]
	v_exp_f32_e32 v28, v28
	v_exp_f32_e32 v29, v29
	v_exp_f32_e32 v30, v30
	v_exp_f32_e32 v31, v31
	v_exp_f32_e32 v24, v24
	v_exp_f32_e32 v25, v25
	v_exp_f32_e32 v26, v26
	v_exp_f32_e32 v27, v27
	v_pk_mul_f32 v[22:23], v[22:23], v[32:33] op_sel_hi:[1,0]
	v_pk_mul_f32 v[20:21], v[20:21], v[32:33] op_sel_hi:[1,0]
	v_pk_add_f32 v[30:31], v[30:31], 1.0 op_sel_hi:[1,0]
	v_pk_add_f32 v[28:29], v[28:29], 1.0 op_sel_hi:[1,0]
	v_pk_add_f32 v[24:25], v[24:25], 1.0 op_sel_hi:[1,0]
	v_pk_mul_f32 v[18:19], v[18:19], v[32:33] op_sel_hi:[1,0]
	v_pk_mul_f32 v[16:17], v[16:17], v[32:33] op_sel_hi:[1,0]
	v_exp_f32_e32 v20, v20
	v_exp_f32_e32 v21, v21
	v_exp_f32_e32 v22, v22
	v_exp_f32_e32 v23, v23
	v_pk_add_f32 v[26:27], v[26:27], 1.0 op_sel_hi:[1,0]
	v_rcp_f32_e32 v28, v28
	v_rcp_f32_e32 v29, v29
	v_rcp_f32_e32 v30, v30
	v_rcp_f32_e32 v31, v31
	v_rcp_f32_e32 v34, v24
	v_rcp_f32_e32 v35, v25
	v_exp_f32_e32 v16, v16
	v_exp_f32_e32 v18, v18
	v_exp_f32_e32 v19, v19
	v_exp_f32_e32 v17, v17
	v_rcp_f32_e32 v36, v26
	v_rcp_f32_e32 v37, v27
	s_waitcnt vmcnt(14)
;     __device__ __forceinline__ void operator()(const f32x4 (&acc)[2][2][4][2], const Unit& u, int wr, int wc, int fr, int fq) const {
;     ...
;             for (int m = 0; m < 4; ++m) { const int row = row0 + ai * HALF + m * 16; const float r = rs[ai][m];
; #pragma unroll
;                 for (int bj = 0; bj < 2; ++bj) { const size_t off = (size_t)row * DM + col0 + bj * HALF;
;                     const u32x4 pr = prv[m][bj], xb = xbv[m][bj];
;                     const float rl = -LOG2E * r;
;                     const f32x4 t0 = acc[ai][bj][m][0] * rl, t1 = acc[ai][bj][m][1] * rl;
;                     const f32x4 d0 = (f32x4){__builtin_amdgcn_exp2f(t0[0]), __builtin_amdgcn_exp2f(t0[1]), __builtin_amdgcn_exp2f(t0[2]), __builtin_amdgcn_exp2f(t0[3])} + 1.f;
;                     const f32x4 d1 = (f32x4){__builtin_amdgcn_exp2f(t1[0]), __builtin_amdgcn_exp2f(t1[1]), __builtin_amdgcn_exp2f(t1[2]), __builtin_amdgcn_exp2f(t1[3])} + 1.f;
;                     const f32x4 s0 = (f32x4){__builtin_amdgcn_rcpf(d0[0]), __builtin_amdgcn_rcpf(d0[1]), __builtin_amdgcn_rcpf(d0[2]), __builtin_amdgcn_rcpf(d0[3])}, s1 = (f32x4){__builtin_amdgcn_rcpf(d1[0]), __builtin_amdgcn_rcpf(d1[1]), __builtin_amdgcn_rcpf(d1[2]), __builtin_amdgcn_rcpf(d1[3])};
;                     const f32x4 x0 = (f32x4){__builtin_bit_cast(float, xb.x << 16), __builtin_bit_cast(float, xb.x & 0xffff0000u), __builtin_bit_cast(float, xb.y << 16), __builtin_bit_cast(float, xb.y & 0xffff0000u)};
;                     const f32x4 x1 = (f32x4){__builtin_bit_cast(float, xb.z << 16), __builtin_bit_cast(float, xb.z & 0xffff0000u), __builtin_bit_cast(float, xb.w << 16), __builtin_bit_cast(float, xb.w & 0xffff0000u)};
;                     const f32x4 p0 = (f32x4){__builtin_bit_cast(float, pr.x << 16), __builtin_bit_cast(float, pr.x & 0xffff0000u), __builtin_bit_cast(float, pr.y << 16), __builtin_bit_cast(float, pr.y & 0xffff0000u)};
;                     const f32x4 p1 = (f32x4){__builtin_bit_cast(float, pr.z << 16), __builtin_bit_cast(float, pr.z & 0xffff0000u), __builtin_bit_cast(float, pr.w << 16), __builtin_bit_cast(float, pr.w & 0xffff0000u)};
;                     const f32x4 o0 = s0 * p0 + x0, o1 = s1 * p1 + x1;
;                     __builtin_nontemporal_store(o0, (f32x4*)(out + off)); __builtin_nontemporal_store(o1, (f32x4*)(out + off + 4)); } }
	v_lshlrev_b32_e32 v24, 16, v92
	v_and_b32_e32 v25, 0xffff0000, v92
	v_lshlrev_b32_e32 v26, 16, v93
	v_and_b32_e32 v27, 0xffff0000, v93
	v_lshlrev_b32_e32 v38, 16, v94
	v_and_b32_e32 v39, 0xffff0000, v94
	v_and_b32_e32 v43, 0xffff0000, v88
	v_lshlrev_b32_e32 v44, 16, v89
	v_and_b32_e32 v45, 0xffff0000, v89
	v_lshlrev_b32_e32 v46, 16, v90
	v_and_b32_e32 v47, 0xffff0000, v90
	v_pk_add_f32 v[22:23], v[22:23], 1.0 op_sel_hi:[1,0]
	v_pk_add_f32 v[20:21], v[20:21], 1.0 op_sel_hi:[1,0]
	v_lshlrev_b32_e32 v40, 16, v95
	v_and_b32_e32 v41, 0xffff0000, v95
	v_lshlrev_b32_e32 v48, 16, v91
	v_and_b32_e32 v49, 0xffff0000, v91
	v_pk_fma_f32 v[26:27], v[30:31], v[44:45], v[26:27]
	v_pk_fma_f32 v[24:25], v[28:29], v[42:43], v[24:25]
	v_pk_fma_f32 v[28:29], v[34:35], v[46:47], v[38:39]
	v_lshl_add_u64 v[34:35], v[114:115], 2, s[50:51]
	v_pk_add_f32 v[18:19], v[18:19], 1.0 op_sel_hi:[1,0]
	v_pk_add_f32 v[16:17], v[16:17], 1.0 op_sel_hi:[1,0]
	v_rcp_f32_e32 v20, v20
	v_rcp_f32_e32 v21, v21
	v_rcp_f32_e32 v22, v22
	v_rcp_f32_e32 v23, v23
	v_pk_fma_f32 v[30:31], v[36:37], v[48:49], v[40:41]
	global_store_dwordx4 v[34:35], v[24:27], off nt
	global_store_dwordx4 v[34:35], v[28:31], off offset:16 nt
	s_waitcnt vmcnt(15)
	v_lshlrev_b32_e32 v32, 16, v80
	v_rcp_f32_e32 v24, v16
	v_rcp_f32_e32 v25, v17
	v_rcp_f32_e32 v26, v18
	v_rcp_f32_e32 v27, v19
	s_waitcnt vmcnt(14)
	v_lshlrev_b32_e32 v16, 16, v84
	v_and_b32_e32 v17, 0xffff0000, v84
	v_lshlrev_b32_e32 v18, 16, v85
	v_and_b32_e32 v19, 0xffff0000, v85
	v_and_b32_e32 v33, 0xffff0000, v80
	v_lshlrev_b32_e32 v36, 16, v81
	v_and_b32_e32 v37, 0xffff0000, v81
	v_lshlrev_b32_e32 v28, 16, v86
	v_and_b32_e32 v29, 0xffff0000, v86
	v_lshlrev_b32_e32 v30, 16, v87
	v_and_b32_e32 v31, 0xffff0000, v87
	v_lshlrev_b32_e32 v38, 16, v82
	v_and_b32_e32 v39, 0xffff0000, v82
	v_lshlrev_b32_e32 v40, 16, v83
	v_and_b32_e32 v41, 0xffff0000, v83
	v_pk_fma_f32 v[18:19], v[22:23], v[36:37], v[18:19]
	v_pk_fma_f32 v[16:17], v[20:21], v[32:33], v[16:17]
	v_pk_fma_f32 v[22:23], v[26:27], v[40:41], v[30:31]
	v_pk_fma_f32 v[20:21], v[24:25], v[38:39], v[28:29]
	global_store_dwordx4 v[34:35], v[16:19], off offset:512 nt
	global_store_dwordx4 v[34:35], v[20:23], off offset:528 nt
	s_waitcnt vmcnt(15)
	v_lshlrev_b32_e32 v26, 16, v72
	v_mul_f32_e32 v16, 0xbfb8aa3b, v179
	v_pk_mul_f32 v[14:15], v[14:15], v[16:17] op_sel_hi:[1,0]
	v_pk_mul_f32 v[12:13], v[12:13], v[16:17] op_sel_hi:[1,0]
	v_pk_mul_f32 v[8:9], v[8:9], v[16:17] op_sel_hi:[1,0]
	v_pk_mul_f32 v[10:11], v[10:11], v[16:17] op_sel_hi:[1,0]
	v_exp_f32_e32 v12, v12
	v_exp_f32_e32 v13, v13
	v_exp_f32_e32 v14, v14
	v_exp_f32_e32 v15, v15
	v_exp_f32_e32 v8, v8
	v_exp_f32_e32 v9, v9
	v_exp_f32_e32 v10, v10
	v_exp_f32_e32 v11, v11
	v_pk_mul_f32 v[6:7], v[6:7], v[16:17] op_sel_hi:[1,0]
	v_pk_mul_f32 v[4:5], v[4:5], v[16:17] op_sel_hi:[1,0]
	v_pk_add_f32 v[14:15], v[14:15], 1.0 op_sel_hi:[1,0]
	v_pk_add_f32 v[12:13], v[12:13], 1.0 op_sel_hi:[1,0]
	v_pk_add_f32 v[8:9], v[8:9], 1.0 op_sel_hi:[1,0]
	v_pk_mul_f32 v[2:3], v[2:3], v[16:17] op_sel_hi:[1,0]
	v_pk_mul_f32 v[0:1], v[0:1], v[16:17] op_sel_hi:[1,0]
	v_exp_f32_e32 v4, v4
	v_exp_f32_e32 v5, v5
	v_exp_f32_e32 v6, v6
	v_exp_f32_e32 v7, v7
	v_pk_add_f32 v[10:11], v[10:11], 1.0 op_sel_hi:[1,0]
	v_rcp_f32_e32 v12, v12
	v_rcp_f32_e32 v13, v13
	v_rcp_f32_e32 v14, v14
	v_rcp_f32_e32 v15, v15
	v_rcp_f32_e32 v18, v8
	v_rcp_f32_e32 v19, v9
	v_exp_f32_e32 v0, v0
	v_exp_f32_e32 v2, v2
	v_exp_f32_e32 v3, v3
	v_exp_f32_e32 v1, v1
	v_rcp_f32_e32 v20, v10
	v_rcp_f32_e32 v21, v11
	s_waitcnt vmcnt(14)
	v_lshlrev_b32_e32 v8, 16, v76
	v_and_b32_e32 v9, 0xffff0000, v76
	v_lshlrev_b32_e32 v10, 16, v77
	v_and_b32_e32 v11, 0xffff0000, v77
	v_lshlrev_b32_e32 v22, 16, v78
	v_and_b32_e32 v23, 0xffff0000, v78
	v_and_b32_e32 v27, 0xffff0000, v72
	v_lshlrev_b32_e32 v28, 16, v73
	v_and_b32_e32 v29, 0xffff0000, v73
	v_lshlrev_b32_e32 v30, 16, v74
	v_and_b32_e32 v31, 0xffff0000, v74
	v_pk_add_f32 v[6:7], v[6:7], 1.0 op_sel_hi:[1,0]
	v_pk_add_f32 v[4:5], v[4:5], 1.0 op_sel_hi:[1,0]
	v_lshlrev_b32_e32 v24, 16, v79
	v_and_b32_e32 v25, 0xffff0000, v79
	v_lshlrev_b32_e32 v32, 16, v75
	v_and_b32_e32 v33, 0xffff0000, v75
	v_pk_fma_f32 v[10:11], v[14:15], v[28:29], v[10:11]
	v_pk_fma_f32 v[8:9], v[12:13], v[26:27], v[8:9]
	v_pk_fma_f32 v[12:13], v[18:19], v[30:31], v[22:23]
	v_lshl_add_u64 v[18:19], v[112:113], 2, s[50:51]
	v_pk_add_f32 v[2:3], v[2:3], 1.0 op_sel_hi:[1,0]
	v_pk_add_f32 v[0:1], v[0:1], 1.0 op_sel_hi:[1,0]
	v_rcp_f32_e32 v4, v4
	v_rcp_f32_e32 v5, v5
	v_rcp_f32_e32 v6, v6
	v_rcp_f32_e32 v7, v7
	v_pk_fma_f32 v[14:15], v[20:21], v[32:33], v[24:25]
	global_store_dwordx4 v[18:19], v[8:11], off nt
	global_store_dwordx4 v[18:19], v[12:15], off offset:16 nt
	s_waitcnt vmcnt(15)
	v_lshlrev_b32_e32 v16, 16, v64
	v_rcp_f32_e32 v8, v0
	v_rcp_f32_e32 v9, v1
	v_rcp_f32_e32 v10, v2
	v_rcp_f32_e32 v11, v3
	s_waitcnt vmcnt(14)
	v_lshlrev_b32_e32 v0, 16, v68
	v_and_b32_e32 v1, 0xffff0000, v68
	v_lshlrev_b32_e32 v2, 16, v69
	v_and_b32_e32 v3, 0xffff0000, v69
	v_and_b32_e32 v17, 0xffff0000, v64
	v_lshlrev_b32_e32 v20, 16, v65
	v_and_b32_e32 v21, 0xffff0000, v65
	v_lshlrev_b32_e32 v12, 16, v70
	v_and_b32_e32 v13, 0xffff0000, v70
	v_lshlrev_b32_e32 v14, 16, v71
	v_and_b32_e32 v15, 0xffff0000, v71
	v_lshlrev_b32_e32 v22, 16, v66
	v_and_b32_e32 v23, 0xffff0000, v66
	v_lshlrev_b32_e32 v24, 16, v67
	v_and_b32_e32 v25, 0xffff0000, v67
	v_pk_fma_f32 v[2:3], v[6:7], v[20:21], v[2:3]
	v_pk_fma_f32 v[0:1], v[4:5], v[16:17], v[0:1]
	s_andn2_b64 vcc, exec, s[0:1]
	s_mov_b64 s[0:1], -1
	v_pk_fma_f32 v[6:7], v[10:11], v[24:25], v[14:15]
	v_pk_fma_f32 v[4:5], v[8:9], v[22:23], v[12:13]
	global_store_dwordx4 v[18:19], v[0:3], off offset:512 nt
	global_store_dwordx4 v[18:19], v[4:7], off offset:528 nt
	s_cbranch_vccnz .LBB0_1025
	s_andn2_b64 vcc, exec, s[10:11]
	s_cbranch_vccnz .LBB0_1024
	s_barrier
	s_branch .LBB0_1024
